# atomic-layout fix + P9 second split on WGs 32-63 + phase 2 rewritten (4-row batches, loads in flight) + write-through (sc1) 16B contiguous stores in phases 2,4,13
# speedup vs baseline: 1.0739x; 1.0079x over previous
.LBB0_441:
	v_writelane_b32 v254, s76, 41
	s_cmp_lt_i32 s68, 3
	s_cselect_b64 s[2:3], -1, 0
	v_writelane_b32 v254, s77, 42
	v_writelane_b32 v254, s78, 43
	v_writelane_b32 v254, s79, 44
	s_cmp_gt_i32 s69, 2
	v_writelane_b32 v254, s80, 45
	s_cselect_b64 s[4:5], -1, 0
	v_writelane_b32 v254, s81, 46
	s_and_b64 s[2:3], s[2:3], s[4:5]
	v_writelane_b32 v254, s82, 47
	s_andn2_b64 vcc, exec, s[2:3]
	v_writelane_b32 v254, s83, 48
	s_mov_b64 s[36:37], s[84:85]
	s_cbranch_vccnz .LBB0_519
	s_mov_b32 s29, 0
	v_mov_b32_e32 v7, 0
	s_lshl_b64 s[2:3], s[28:29], 9
	v_mov_b32_e32 v35, v7
	v_lshl_add_u64 v[8:9], s[2:3], 0, v[34:35]
	s_mov_b64 s[2:3], 0x210000
	v_cmp_gt_u64_e32 vcc, s[2:3], v[8:9]
	s_and_saveexec_b64 s[8:9], vcc
	s_cbranch_execz .LBB0_451
	s_cmpk_lg_i32 s88, 0x100
	s_cbranch_scc1 .Lp2_orig
	s_add_u32 s10, s34, 0x8240000
	s_addc_u32 s11, s35, 0
	s_add_u32 s12, s34, 0x9122200
	s_addc_u32 s13, s35, 0
	v_readlane_b32 s14, v254, 5
	v_readlane_b32 s15, v254, 6
	v_readlane_b32 s16, v254, 7
	v_readlane_b32 s17, v254, 8
	v_readfirstlane_b32 s4, v34
	v_and_b32_e32 v36, 0xff, v34
	v_lshlrev_b32_e32 v37, 4, v36
	v_lshlrev_b32_e32 v36, 5, v36
	s_lshr_b32 s4, s4, 8
	s_lshl1_add_u32 s4, s28, s4
	s_lshl_b32 s2, s4, 13
	s_add_u32 s14, s14, s2
	s_addc_u32 s15, s15, 0
	s_lshl_b32 s3, s4, 12
	s_add_u32 s12, s12, s3
	s_addc_u32 s13, s13, 0
	s_add_u32 s18, s10, 0x0
	s_addc_u32 s19, s11, 0
	s_add_u32 s20, s18, 0x2000
	s_addc_u32 s21, s19, 0
	global_load_dwordx4 v[40:43], v36, s[18:19]
	global_load_dwordx4 v[44:47], v36, s[18:19] offset:16
	global_load_dwordx4 v[48:51], v36, s[20:21]
	global_load_dwordx4 v[52:55], v36, s[20:21] offset:16
	s_add_u32 s22, s14, 0x0
	s_addc_u32 s23, s15, 0
	global_load_dwordx4 v[56:59], v36, s[22:23] nt
	global_load_dwordx4 v[60:63], v36, s[22:23] offset:16 nt
	s_add_u32 s24, s14, 0x400000
	s_addc_u32 s25, s15, 0
	global_load_dwordx4 v[64:67], v36, s[24:25] nt
	global_load_dwordx4 v[68:71], v36, s[24:25] offset:16 nt
	s_add_u32 s26, s14, 0x800000
	s_addc_u32 s27, s15, 0
	global_load_dwordx4 v[72:75], v36, s[26:27] nt
	global_load_dwordx4 v[76:79], v36, s[26:27] offset:16 nt
	s_add_u32 s30, s14, 0xc00000
	s_addc_u32 s31, s15, 0
	global_load_dwordx4 v[80:83], v36, s[30:31] nt
	global_load_dwordx4 v[84:87], v36, s[30:31] offset:16 nt
	s_add_u32 s18, s10, 0xc000
	s_addc_u32 s19, s11, 0
	s_add_u32 s20, s18, 0x2000
	s_addc_u32 s21, s19, 0
	global_load_dwordx4 v[90:93], v36, s[18:19]
	global_load_dwordx4 v[94:97], v36, s[18:19] offset:16
	global_load_dwordx4 v[98:101], v36, s[20:21]
	global_load_dwordx4 v[102:105], v36, s[20:21] offset:16
	s_add_u32 s22, s14, 0x1000000
	s_addc_u32 s23, s15, 0
	global_load_dwordx4 v[106:109], v36, s[22:23] nt
	global_load_dwordx4 v[110:113], v36, s[22:23] offset:16 nt
	s_add_u32 s24, s14, 0x1400000
	s_addc_u32 s25, s15, 0
	global_load_dwordx4 v[114:117], v36, s[24:25] nt
	global_load_dwordx4 v[118:121], v36, s[24:25] offset:16 nt
	s_add_u32 s26, s14, 0x1800000
	s_addc_u32 s27, s15, 0
	global_load_dwordx4 v[122:125], v36, s[26:27] nt
	global_load_dwordx4 v[126:129], v36, s[26:27] offset:16 nt
	s_add_u32 s30, s14, 0x1c00000
	s_addc_u32 s31, s15, 0
	global_load_dwordx4 v[130:133], v36, s[30:31] nt
	global_load_dwordx4 v[134:137], v36, s[30:31] offset:16 nt
	s_waitcnt vmcnt(12)
	v_pk_add_f32 v[48:49], v[48:49], 1.0 op_sel_hi:[1,0]
	v_pk_add_f32 v[50:51], v[50:51], 1.0 op_sel_hi:[1,0]
	v_pk_add_f32 v[52:53], v[52:53], 1.0 op_sel_hi:[1,0]
	v_pk_add_f32 v[54:55], v[54:55], 1.0 op_sel_hi:[1,0]
	v_pk_fma_f32 v[56:57], v[56:57], v[48:49], v[40:41]
	v_pk_fma_f32 v[58:59], v[58:59], v[50:51], v[42:43]
	v_pk_fma_f32 v[60:61], v[60:61], v[52:53], v[44:45]
	v_pk_fma_f32 v[62:63], v[62:63], v[54:55], v[46:47]
	v_pk_fma_f32 v[64:65], v[64:65], v[48:49], v[40:41]
	v_pk_fma_f32 v[66:67], v[66:67], v[50:51], v[42:43]
	v_pk_fma_f32 v[68:69], v[68:69], v[52:53], v[44:45]
	v_pk_fma_f32 v[70:71], v[70:71], v[54:55], v[46:47]
	v_pk_fma_f32 v[72:73], v[72:73], v[48:49], v[40:41]
	v_pk_fma_f32 v[74:75], v[74:75], v[50:51], v[42:43]
	v_pk_fma_f32 v[76:77], v[76:77], v[52:53], v[44:45]
	v_pk_fma_f32 v[78:79], v[78:79], v[54:55], v[46:47]
	v_pk_fma_f32 v[80:81], v[80:81], v[48:49], v[40:41]
	v_pk_fma_f32 v[82:83], v[82:83], v[50:51], v[42:43]
	v_pk_fma_f32 v[84:85], v[84:85], v[52:53], v[44:45]
	v_pk_fma_f32 v[86:87], v[86:87], v[54:55], v[46:47]
	s_nop 0
	v_cvt_pk_bf16_f32 v140, v56, v57
	v_cvt_pk_bf16_f32 v141, v58, v59
	v_cvt_pk_bf16_f32 v142, v60, v61
	v_cvt_pk_bf16_f32 v143, v62, v63
	v_cvt_pk_bf16_f32 v144, v64, v65
	v_cvt_pk_bf16_f32 v145, v66, v67
	v_cvt_pk_bf16_f32 v146, v68, v69
	v_cvt_pk_bf16_f32 v147, v70, v71
	v_cvt_pk_bf16_f32 v148, v72, v73
	v_cvt_pk_bf16_f32 v149, v74, v75
	v_cvt_pk_bf16_f32 v150, v76, v77
	v_cvt_pk_bf16_f32 v151, v78, v79
	v_cvt_pk_bf16_f32 v152, v80, v81
	v_cvt_pk_bf16_f32 v153, v82, v83
	v_cvt_pk_bf16_f32 v154, v84, v85
	v_cvt_pk_bf16_f32 v155, v86, v87
	s_add_u32 s40, s12, 0x0
	s_addc_u32 s41, s13, 0
	global_store_dwordx4 v37, v[140:143], s[40:41] sc1
	s_add_u32 s42, s12, 0x200000
	s_addc_u32 s43, s13, 0
	global_store_dwordx4 v37, v[144:147], s[42:43] sc1
	s_add_u32 s6, s12, 0x400000
	s_addc_u32 s7, s13, 0
	global_store_dwordx4 v37, v[148:151], s[6:7] sc1
	s_add_u32 s2, s12, 0x600000
	s_addc_u32 s3, s13, 0
	global_store_dwordx4 v37, v[152:155], s[2:3] sc1
	s_add_u32 s18, s10, 0x18000
	s_addc_u32 s19, s11, 0
	s_add_u32 s20, s18, 0x2000
	s_addc_u32 s21, s19, 0
	global_load_dwordx4 v[40:43], v36, s[18:19]
	global_load_dwordx4 v[44:47], v36, s[18:19] offset:16
	global_load_dwordx4 v[48:51], v36, s[20:21]
	global_load_dwordx4 v[52:55], v36, s[20:21] offset:16
	s_add_u32 s22, s14, 0x2000000
	s_addc_u32 s23, s15, 0
	global_load_dwordx4 v[56:59], v36, s[22:23] nt
	global_load_dwordx4 v[60:63], v36, s[22:23] offset:16 nt
	s_add_u32 s24, s14, 0x2400000
	s_addc_u32 s25, s15, 0
	global_load_dwordx4 v[64:67], v36, s[24:25] nt
	global_load_dwordx4 v[68:71], v36, s[24:25] offset:16 nt
	s_add_u32 s26, s14, 0x2800000
	s_addc_u32 s27, s15, 0
	global_load_dwordx4 v[72:75], v36, s[26:27] nt
	global_load_dwordx4 v[76:79], v36, s[26:27] offset:16 nt
	s_add_u32 s30, s14, 0x2c00000
	s_addc_u32 s31, s15, 0
	global_load_dwordx4 v[80:83], v36, s[30:31] nt
	global_load_dwordx4 v[84:87], v36, s[30:31] offset:16 nt
	s_waitcnt vmcnt(16)
	v_pk_add_f32 v[98:99], v[98:99], 1.0 op_sel_hi:[1,0]
	v_pk_add_f32 v[100:101], v[100:101], 1.0 op_sel_hi:[1,0]
	v_pk_add_f32 v[102:103], v[102:103], 1.0 op_sel_hi:[1,0]
	v_pk_add_f32 v[104:105], v[104:105], 1.0 op_sel_hi:[1,0]
	v_pk_fma_f32 v[106:107], v[106:107], v[98:99], v[90:91]
	v_pk_fma_f32 v[108:109], v[108:109], v[100:101], v[92:93]
	v_pk_fma_f32 v[110:111], v[110:111], v[102:103], v[94:95]
	v_pk_fma_f32 v[112:113], v[112:113], v[104:105], v[96:97]
	v_pk_fma_f32 v[114:115], v[114:115], v[98:99], v[90:91]
	v_pk_fma_f32 v[116:117], v[116:117], v[100:101], v[92:93]
	v_pk_fma_f32 v[118:119], v[118:119], v[102:103], v[94:95]
	v_pk_fma_f32 v[120:121], v[120:121], v[104:105], v[96:97]
	v_pk_fma_f32 v[122:123], v[122:123], v[98:99], v[90:91]
	v_pk_fma_f32 v[124:125], v[124:125], v[100:101], v[92:93]
	v_pk_fma_f32 v[126:127], v[126:127], v[102:103], v[94:95]
	v_pk_fma_f32 v[128:129], v[128:129], v[104:105], v[96:97]
	v_pk_fma_f32 v[130:131], v[130:131], v[98:99], v[90:91]
	v_pk_fma_f32 v[132:133], v[132:133], v[100:101], v[92:93]
	v_pk_fma_f32 v[134:135], v[134:135], v[102:103], v[94:95]
	v_pk_fma_f32 v[136:137], v[136:137], v[104:105], v[96:97]
	s_nop 0
	v_cvt_pk_bf16_f32 v140, v106, v107
	v_cvt_pk_bf16_f32 v141, v108, v109
	v_cvt_pk_bf16_f32 v142, v110, v111
	v_cvt_pk_bf16_f32 v143, v112, v113
	v_cvt_pk_bf16_f32 v144, v114, v115
	v_cvt_pk_bf16_f32 v145, v116, v117
	v_cvt_pk_bf16_f32 v146, v118, v119
	v_cvt_pk_bf16_f32 v147, v120, v121
	v_cvt_pk_bf16_f32 v148, v122, v123
	v_cvt_pk_bf16_f32 v149, v124, v125
	v_cvt_pk_bf16_f32 v150, v126, v127
	v_cvt_pk_bf16_f32 v151, v128, v129
	v_cvt_pk_bf16_f32 v152, v130, v131
	v_cvt_pk_bf16_f32 v153, v132, v133
	v_cvt_pk_bf16_f32 v154, v134, v135
	v_cvt_pk_bf16_f32 v155, v136, v137
	s_add_u32 s40, s12, 0x800000
	s_addc_u32 s41, s13, 0
	global_store_dwordx4 v37, v[140:143], s[40:41] sc1
	s_add_u32 s42, s12, 0xa00000
	s_addc_u32 s43, s13, 0
	global_store_dwordx4 v37, v[144:147], s[42:43] sc1
	s_add_u32 s6, s12, 0xc00000
	s_addc_u32 s7, s13, 0
	global_store_dwordx4 v37, v[148:151], s[6:7] sc1
	s_add_u32 s2, s12, 0xe00000
	s_addc_u32 s3, s13, 0
	global_store_dwordx4 v37, v[152:155], s[2:3] sc1
	s_add_u32 s18, s10, 0x24000
	s_addc_u32 s19, s11, 0
	s_add_u32 s20, s18, 0x2000
	s_addc_u32 s21, s19, 0
	global_load_dwordx4 v[90:93], v36, s[18:19]
	global_load_dwordx4 v[94:97], v36, s[18:19] offset:16
	global_load_dwordx4 v[98:101], v36, s[20:21]
	global_load_dwordx4 v[102:105], v36, s[20:21] offset:16
	s_add_u32 s22, s14, 0x3000000
	s_addc_u32 s23, s15, 0
	global_load_dwordx4 v[106:109], v36, s[22:23] nt
	global_load_dwordx4 v[110:113], v36, s[22:23] offset:16 nt
	s_add_u32 s24, s14, 0x3400000
	s_addc_u32 s25, s15, 0
	global_load_dwordx4 v[114:117], v36, s[24:25] nt
	global_load_dwordx4 v[118:121], v36, s[24:25] offset:16 nt
	s_add_u32 s26, s14, 0x3800000
	s_addc_u32 s27, s15, 0
	global_load_dwordx4 v[122:125], v36, s[26:27] nt
	global_load_dwordx4 v[126:129], v36, s[26:27] offset:16 nt
	s_add_u32 s30, s14, 0x3c00000
	s_addc_u32 s31, s15, 0
	global_load_dwordx4 v[130:133], v36, s[30:31] nt
	global_load_dwordx4 v[134:137], v36, s[30:31] offset:16 nt
	s_waitcnt vmcnt(16)
	v_pk_add_f32 v[48:49], v[48:49], 1.0 op_sel_hi:[1,0]
	v_pk_add_f32 v[50:51], v[50:51], 1.0 op_sel_hi:[1,0]
	v_pk_add_f32 v[52:53], v[52:53], 1.0 op_sel_hi:[1,0]
	v_pk_add_f32 v[54:55], v[54:55], 1.0 op_sel_hi:[1,0]
	v_pk_fma_f32 v[56:57], v[56:57], v[48:49], v[40:41]
	v_pk_fma_f32 v[58:59], v[58:59], v[50:51], v[42:43]
	v_pk_fma_f32 v[60:61], v[60:61], v[52:53], v[44:45]
	v_pk_fma_f32 v[62:63], v[62:63], v[54:55], v[46:47]
	v_pk_fma_f32 v[64:65], v[64:65], v[48:49], v[40:41]
	v_pk_fma_f32 v[66:67], v[66:67], v[50:51], v[42:43]
	v_pk_fma_f32 v[68:69], v[68:69], v[52:53], v[44:45]
	v_pk_fma_f32 v[70:71], v[70:71], v[54:55], v[46:47]
	v_pk_fma_f32 v[72:73], v[72:73], v[48:49], v[40:41]
	v_pk_fma_f32 v[74:75], v[74:75], v[50:51], v[42:43]
	v_pk_fma_f32 v[76:77], v[76:77], v[52:53], v[44:45]
	v_pk_fma_f32 v[78:79], v[78:79], v[54:55], v[46:47]
	v_pk_fma_f32 v[80:81], v[80:81], v[48:49], v[40:41]
	v_pk_fma_f32 v[82:83], v[82:83], v[50:51], v[42:43]
	v_pk_fma_f32 v[84:85], v[84:85], v[52:53], v[44:45]
	v_pk_fma_f32 v[86:87], v[86:87], v[54:55], v[46:47]
	s_nop 0
	v_cvt_pk_bf16_f32 v140, v56, v57
	v_cvt_pk_bf16_f32 v141, v58, v59
	v_cvt_pk_bf16_f32 v142, v60, v61
	v_cvt_pk_bf16_f32 v143, v62, v63
	v_cvt_pk_bf16_f32 v144, v64, v65
	v_cvt_pk_bf16_f32 v145, v66, v67
	v_cvt_pk_bf16_f32 v146, v68, v69
	v_cvt_pk_bf16_f32 v147, v70, v71
	v_cvt_pk_bf16_f32 v148, v72, v73
	v_cvt_pk_bf16_f32 v149, v74, v75
	v_cvt_pk_bf16_f32 v150, v76, v77
	v_cvt_pk_bf16_f32 v151, v78, v79
	v_cvt_pk_bf16_f32 v152, v80, v81
	v_cvt_pk_bf16_f32 v153, v82, v83
	v_cvt_pk_bf16_f32 v154, v84, v85
	v_cvt_pk_bf16_f32 v155, v86, v87
	s_add_u32 s40, s12, 0x1000000
	s_addc_u32 s41, s13, 0
	global_store_dwordx4 v37, v[140:143], s[40:41] sc1
	s_add_u32 s42, s12, 0x1200000
	s_addc_u32 s43, s13, 0
	global_store_dwordx4 v37, v[144:147], s[42:43] sc1
	s_add_u32 s6, s12, 0x1400000
	s_addc_u32 s7, s13, 0
	global_store_dwordx4 v37, v[148:151], s[6:7] sc1
	s_add_u32 s2, s12, 0x1600000
	s_addc_u32 s3, s13, 0
	global_store_dwordx4 v37, v[152:155], s[2:3] sc1
	s_cmpk_gt_u32 s4, 0x7f
	s_cbranch_scc1 .Lp2_w4
	s_mul_i32 s2, s4, 0xc000
	s_add_u32 s2, s2, 0x30000
	s_add_u32 s18, s10, s2
	s_addc_u32 s19, s11, 0
	s_add_u32 s20, s18, 0x2000
	s_addc_u32 s21, s19, 0
	s_lshl_b32 s2, s4, 13
	s_add_u32 s22, s16, s2
	s_addc_u32 s23, s17, 0
	global_load_dwordx4 v[40:43], v36, s[18:19]
	global_load_dwordx4 v[44:47], v36, s[18:19] offset:16
	global_load_dwordx4 v[48:51], v36, s[20:21]
	global_load_dwordx4 v[52:55], v36, s[20:21] offset:16
	global_load_dwordx4 v[56:59], v36, s[22:23] nt
	global_load_dwordx4 v[60:63], v36, s[22:23] offset:16 nt
	s_waitcnt vmcnt(10)
	s_branch .Lp2_c3
.Lp2_w4:
	s_waitcnt vmcnt(4)
.Lp2_c3:
	v_pk_add_f32 v[98:99], v[98:99], 1.0 op_sel_hi:[1,0]
	v_pk_add_f32 v[100:101], v[100:101], 1.0 op_sel_hi:[1,0]
	v_pk_add_f32 v[102:103], v[102:103], 1.0 op_sel_hi:[1,0]
	v_pk_add_f32 v[104:105], v[104:105], 1.0 op_sel_hi:[1,0]
	v_pk_fma_f32 v[106:107], v[106:107], v[98:99], v[90:91]
	v_pk_fma_f32 v[108:109], v[108:109], v[100:101], v[92:93]
	v_pk_fma_f32 v[110:111], v[110:111], v[102:103], v[94:95]
	v_pk_fma_f32 v[112:113], v[112:113], v[104:105], v[96:97]
	v_pk_fma_f32 v[114:115], v[114:115], v[98:99], v[90:91]
	v_pk_fma_f32 v[116:117], v[116:117], v[100:101], v[92:93]
	v_pk_fma_f32 v[118:119], v[118:119], v[102:103], v[94:95]
	v_pk_fma_f32 v[120:121], v[120:121], v[104:105], v[96:97]
	v_pk_fma_f32 v[122:123], v[122:123], v[98:99], v[90:91]
	v_pk_fma_f32 v[124:125], v[124:125], v[100:101], v[92:93]
	v_pk_fma_f32 v[126:127], v[126:127], v[102:103], v[94:95]
	v_pk_fma_f32 v[128:129], v[128:129], v[104:105], v[96:97]
	v_pk_fma_f32 v[130:131], v[130:131], v[98:99], v[90:91]
	v_pk_fma_f32 v[132:133], v[132:133], v[100:101], v[92:93]
	v_pk_fma_f32 v[134:135], v[134:135], v[102:103], v[94:95]
	v_pk_fma_f32 v[136:137], v[136:137], v[104:105], v[96:97]
	s_nop 0
	v_cvt_pk_bf16_f32 v140, v106, v107
	v_cvt_pk_bf16_f32 v141, v108, v109
	v_cvt_pk_bf16_f32 v142, v110, v111
	v_cvt_pk_bf16_f32 v143, v112, v113
	v_cvt_pk_bf16_f32 v144, v114, v115
	v_cvt_pk_bf16_f32 v145, v116, v117
	v_cvt_pk_bf16_f32 v146, v118, v119
	v_cvt_pk_bf16_f32 v147, v120, v121
	v_cvt_pk_bf16_f32 v148, v122, v123
	v_cvt_pk_bf16_f32 v149, v124, v125
	v_cvt_pk_bf16_f32 v150, v126, v127
	v_cvt_pk_bf16_f32 v151, v128, v129
	v_cvt_pk_bf16_f32 v152, v130, v131
	v_cvt_pk_bf16_f32 v153, v132, v133
	v_cvt_pk_bf16_f32 v154, v134, v135
	v_cvt_pk_bf16_f32 v155, v136, v137
	s_add_u32 s40, s12, 0x1800000
	s_addc_u32 s41, s13, 0
	global_store_dwordx4 v37, v[140:143], s[40:41] sc1
	s_add_u32 s42, s12, 0x1a00000
	s_addc_u32 s43, s13, 0
	global_store_dwordx4 v37, v[144:147], s[42:43] sc1
	s_add_u32 s6, s12, 0x1c00000
	s_addc_u32 s7, s13, 0
	global_store_dwordx4 v37, v[148:151], s[6:7] sc1
	s_add_u32 s2, s12, 0x1e00000
	s_addc_u32 s3, s13, 0
	global_store_dwordx4 v37, v[152:155], s[2:3] sc1
	s_cmpk_gt_u32 s4, 0xff
	s_cbranch_scc1 .LBB0_451
	s_add_u32 s40, s12, 0x2000000
	s_addc_u32 s41, s13, 0
	s_cmpk_gt_u32 s4, 0x7f
	s_cbranch_scc1 .Lp2_pad
	s_waitcnt vmcnt(4)
	v_pk_add_f32 v[48:49], v[48:49], 1.0 op_sel_hi:[1,0]
	v_pk_add_f32 v[50:51], v[50:51], 1.0 op_sel_hi:[1,0]
	v_pk_add_f32 v[52:53], v[52:53], 1.0 op_sel_hi:[1,0]
	v_pk_add_f32 v[54:55], v[54:55], 1.0 op_sel_hi:[1,0]
	v_pk_fma_f32 v[56:57], v[56:57], v[48:49], v[40:41]
	v_pk_fma_f32 v[58:59], v[58:59], v[50:51], v[42:43]
	v_pk_fma_f32 v[60:61], v[60:61], v[52:53], v[44:45]
	v_pk_fma_f32 v[62:63], v[62:63], v[54:55], v[46:47]
	s_nop 0
	v_cvt_pk_bf16_f32 v140, v56, v57
	v_cvt_pk_bf16_f32 v141, v58, v59
	v_cvt_pk_bf16_f32 v142, v60, v61
	v_cvt_pk_bf16_f32 v143, v62, v63
	global_store_dwordx4 v37, v[140:143], s[40:41] sc1
	s_branch .LBB0_451
.Lp2_pad:
	v_mov_b32_e32 v140, 0
	v_mov_b32_e32 v141, 0
	v_mov_b32_e32 v142, 0
	v_mov_b32_e32 v143, 0
	global_store_dwordx4 v37, v[140:143], s[40:41] sc1
	s_branch .LBB0_451
.Lp2_orig:
	s_add_u32 s10, s34, 0x8240000
	s_addc_u32 s11, s35, 0
	s_add_u32 s12, s34, 0x9122200
	s_mov_b32 s2, s88
	s_mov_b32 s3, s29
	v_lshlrev_b32_e32 v1, 3, v34
	s_mov_b32 s24, 0xff000000
	s_addc_u32 s13, s35, 0
	s_lshl_b64 s[14:15], s[2:3], 9
	v_lshl_add_u32 v1, s28, 12, v1
	s_lshl_b32 s2, s88, 12
	s_mov_b64 s[16:17], 0
	s_mov_b64 s[18:19], 0x207fff
	s_mov_b64 s[20:21], 0x200000
	s_mov_b64 s[22:23], 0x1fffff
	s_movk_i32 s25, 0x7ff
	s_mov_b32 s3, 0xc000
	s_mov_b64 s[26:27], 0x2000
	s_movk_i32 s4, 0x2000
	s_mov_b64 s[40:41], 0x20ffff
	s_branch .LBB0_446

.LBB0_613:
	s_or_b64 exec, exec, s[40:41]
	v_mov_b64_e32 v[8:9], s[18:19]
	v_lshl_add_u64 v[18:19], v[18:19], 0, s[10:11]
	v_mad_u64_u32 v[8:9], s[6:7], v25, s54, v[8:9]
	v_cmp_lt_u64_e32 vcc, s[26:27], v[18:19]
	v_lshl_add_u64 v[8:9], v[20:21], 1, v[8:9]
	s_or_b64 s[20:21], vcc, s[20:21]
	global_store_dwordx4 v[8:9], v[4:7], off sc1
	s_andn2_b64 exec, exec, s[20:21]
	s_cbranch_execz .LBB0_686

.LBB0_2012:
	s_add_i32 s56, s88, s56
	s_and_b32 s57, s56, 7
	s_and_b32 s58, s42, 0xffffff00
	s_cmp_lt_i32 s56, 32
	s_cselect_b64 s[14:15], -1, 0
	s_and_b64 s[14:15], s[14:15], exec
	s_cselect_b32 s14, s58, s18
	s_ashr_i32 s15, s14, 31
	s_lshl_b64 s[16:17], s[14:15], 1
	s_lshl_b32 s14, s57, 20
	s_add_u32 s14, s3, s14
	s_addc_u32 s15, s4, 0
	s_add_u32 s14, s14, s16
	s_addc_u32 s15, s15, s17
	s_cmp_lt_i32 s56, 32
	s_cselect_b64 s[18:19], -1, 0
	ds_read_b128 v[18:21], v13
	ds_read_b128 v[22:25], v13 offset:1024
	ds_read_b128 v[26:29], v13 offset:2048
	ds_read_b128 v[30:33], v13 offset:3072
	s_and_b64 s[18:19], s[18:19], exec
	s_cselect_b32 s19, s15, s23
	s_cselect_b32 s18, s14, s22
	s_add_u32 s16, s27, s16
	s_addc_u32 s17, s29, s17
	s_cmp_lt_i32 s56, 32
	s_cselect_b64 s[24:25], -1, 0
	s_and_b64 vcc, s[24:25], exec
	s_cselect_b32 s25, s17, s21
	s_cselect_b32 s24, s16, s20
	s_add_u32 s60, s20, 0x80080
	s_addc_u32 s61, s21, 0
	s_mov_b32 m0, s44
	v_lshl_add_u64 v[68:69], s[60:61], 0, v[136:137]
	ds_read_b128 v[36:39], v14
	ds_read_b128 v[40:43], v14 offset:1024
	ds_read_b128 v[44:47], v14 offset:2048
	ds_read_b128 v[48:51], v14 offset:3072
	ds_read_b128 v[52:55], v14 offset:4096
	ds_read_b128 v[56:59], v14 offset:5120
	ds_read_b128 v[60:63], v14 offset:6144
	ds_read_b128 v[64:67], v14 offset:7168
	global_load_lds_dwordx4 v[68:69], off
	v_lshl_add_u64 v[68:69], s[60:61], 0, v[138:139]
	s_mov_b32 m0, s45
	s_nop 0
	global_load_lds_dwordx4 v[68:69], off
	s_waitcnt lgkmcnt(8)
	s_barrier
	s_waitcnt lgkmcnt(0)
	s_setprio 1
	s_waitcnt lgkmcnt(0)
	v_mfma_f32_16x16x32_bf16 v[68:71], v[36:39], v[18:21], 0
	v_mfma_f32_16x16x32_bf16 v[76:79], v[44:47], v[18:21], 0
	v_mfma_f32_16x16x32_bf16 v[84:87], v[52:55], v[18:21], 0
	v_mfma_f32_16x16x32_bf16 v[18:21], v[60:63], v[18:21], 0
	v_mfma_f32_16x16x32_bf16 v[68:71], v[40:43], v[22:25], v[68:71]
	v_mfma_f32_16x16x32_bf16 v[72:75], v[36:39], v[26:29], 0
	v_mfma_f32_16x16x32_bf16 v[76:79], v[48:51], v[22:25], v[76:79]
	v_mfma_f32_16x16x32_bf16 v[80:83], v[44:47], v[26:29], 0
	v_mfma_f32_16x16x32_bf16 v[84:87], v[56:59], v[22:25], v[84:87]
	v_mfma_f32_16x16x32_bf16 v[88:91], v[52:55], v[26:29], 0
	v_mfma_f32_16x16x32_bf16 v[18:21], v[64:67], v[22:25], v[18:21]
	v_mfma_f32_16x16x32_bf16 v[22:25], v[60:63], v[26:29], 0
	v_mfma_f32_16x16x32_bf16 v[72:75], v[40:43], v[30:33], v[72:75]
	v_mfma_f32_16x16x32_bf16 v[80:83], v[48:51], v[30:33], v[80:83]
	v_mfma_f32_16x16x32_bf16 v[88:91], v[56:59], v[30:33], v[88:91]
	v_mfma_f32_16x16x32_bf16 v[22:25], v[64:67], v[30:33], v[22:25]
	s_setprio 0
	s_barrier
	v_lshl_add_u64 v[132:133], s[22:23], 0, v[136:137]
	s_mov_b32 m0, s46
	v_lshl_add_u64 v[100:101], v[132:133], 0, s[10:11]
	v_lshl_add_u64 v[134:135], s[22:23], 0, v[138:139]
	ds_read_b128 v[26:29], v15
	ds_read_b128 v[30:33], v15 offset:1024
	ds_read_b128 v[92:95], v15 offset:2048
	ds_read_b128 v[96:99], v15 offset:3072
	global_load_lds_dwordx4 v[100:101], off
	v_lshl_add_u64 v[100:101], v[134:135], 0, s[10:11]
	s_mov_b32 m0, s47
	s_nop 0
	global_load_lds_dwordx4 v[100:101], off
	s_barrier
	s_waitcnt lgkmcnt(0)
	s_setprio 1
	s_waitcnt lgkmcnt(0)
	v_mfma_f32_16x16x32_bf16 v[100:103], v[36:39], v[26:29], 0
	v_mfma_f32_16x16x32_bf16 v[36:39], v[36:39], v[92:95], 0
	v_mfma_f32_16x16x32_bf16 v[100:103], v[40:43], v[30:33], v[100:103]
	v_mfma_f32_16x16x32_bf16 v[36:39], v[40:43], v[96:99], v[36:39]
	v_mfma_f32_16x16x32_bf16 v[40:43], v[44:47], v[26:29], 0
	v_mfma_f32_16x16x32_bf16 v[44:47], v[44:47], v[92:95], 0
	v_mfma_f32_16x16x32_bf16 v[40:43], v[48:51], v[30:33], v[40:43]
	v_mfma_f32_16x16x32_bf16 v[44:47], v[48:51], v[96:99], v[44:47]
	v_mfma_f32_16x16x32_bf16 v[48:51], v[52:55], v[26:29], 0
	v_mfma_f32_16x16x32_bf16 v[26:29], v[60:63], v[26:29], 0
	v_mfma_f32_16x16x32_bf16 v[48:51], v[56:59], v[30:33], v[48:51]
	v_mfma_f32_16x16x32_bf16 v[52:55], v[52:55], v[92:95], 0
	v_mfma_f32_16x16x32_bf16 v[26:29], v[64:67], v[30:33], v[26:29]
	v_mfma_f32_16x16x32_bf16 v[30:33], v[60:63], v[92:95], 0
	v_mfma_f32_16x16x32_bf16 v[52:55], v[56:59], v[96:99], v[52:55]
	v_mfma_f32_16x16x32_bf16 v[30:33], v[64:67], v[96:99], v[30:33]
	s_setprio 0
	v_lshl_add_u64 v[140:141], s[20:21], 0, v[136:137]
	s_mov_b32 m0, s26
	v_lshl_add_u64 v[56:57], v[140:141], 0, s[10:11]
	v_lshl_add_u64 v[142:143], s[20:21], 0, v[138:139]
	s_barrier
	global_load_lds_dwordx4 v[56:57], off
	v_lshl_add_u64 v[56:57], v[142:143], 0, s[10:11]
	s_mov_b32 m0, s30
	s_nop 0
	global_load_lds_dwordx4 v[56:57], off
	s_barrier
	s_waitcnt lgkmcnt(0)
	s_setprio 1
	s_setprio 0
	s_barrier
	s_add_u32 s60, s22, 0x80100
	s_addc_u32 s61, s23, 0
	s_mov_b32 m0, s48
	v_lshl_add_u64 v[56:57], s[60:61], 0, v[136:137]
	global_load_lds_dwordx4 v[56:57], off
	v_lshl_add_u64 v[56:57], s[60:61], 0, v[138:139]
	s_mov_b32 m0, s49
	s_nop 0
	global_load_lds_dwordx4 v[56:57], off
	s_waitcnt vmcnt(6)
	s_barrier
	s_setprio 1
	s_setprio 0
	s_barrier
	ds_read_b128 v[56:59], v16
	ds_read_b128 v[60:63], v16 offset:1024
	ds_read_b128 v[64:67], v16 offset:2048
	ds_read_b128 v[92:95], v16 offset:3072
	s_add_u32 s60, s20, 0x80100
	s_addc_u32 s61, s21, 0
	s_mov_b32 m0, s31
	v_lshl_add_u64 v[144:145], s[60:61], 0, v[136:137]
	ds_read_b128 v[96:99], v14 offset:32768
	ds_read_b128 v[104:107], v14 offset:33792
	ds_read_b128 v[108:111], v14 offset:34816
	ds_read_b128 v[112:115], v14 offset:35840
	ds_read_b128 v[116:119], v14 offset:36864
	ds_read_b128 v[120:123], v14 offset:37888
	ds_read_b128 v[124:127], v14 offset:38912
	ds_read_b128 v[128:131], v14 offset:39936
	global_load_lds_dwordx4 v[144:145], off
	v_lshl_add_u64 v[144:145], s[60:61], 0, v[138:139]
	s_mov_b32 m0, s33
	s_nop 0
	global_load_lds_dwordx4 v[144:145], off
	s_waitcnt lgkmcnt(8)
	s_barrier
	s_waitcnt lgkmcnt(0)
	s_setprio 1
	s_waitcnt lgkmcnt(0)
	v_mfma_f32_16x16x32_bf16 v[68:71], v[96:99], v[56:59], v[68:71]
	v_mfma_f32_16x16x32_bf16 v[72:75], v[96:99], v[64:67], v[72:75]
	v_mfma_f32_16x16x32_bf16 v[76:79], v[108:111], v[56:59], v[76:79]
	v_mfma_f32_16x16x32_bf16 v[80:83], v[108:111], v[64:67], v[80:83]
	v_mfma_f32_16x16x32_bf16 v[84:87], v[116:119], v[56:59], v[84:87]
	v_mfma_f32_16x16x32_bf16 v[88:91], v[116:119], v[64:67], v[88:91]
	v_mfma_f32_16x16x32_bf16 v[18:21], v[124:127], v[56:59], v[18:21]
	v_mfma_f32_16x16x32_bf16 v[22:25], v[124:127], v[64:67], v[22:25]
	v_mfma_f32_16x16x32_bf16 v[68:71], v[104:107], v[60:63], v[68:71]
	v_mfma_f32_16x16x32_bf16 v[72:75], v[104:107], v[92:95], v[72:75]
	v_mfma_f32_16x16x32_bf16 v[76:79], v[112:115], v[60:63], v[76:79]
	v_mfma_f32_16x16x32_bf16 v[80:83], v[112:115], v[92:95], v[80:83]
	v_mfma_f32_16x16x32_bf16 v[84:87], v[120:123], v[60:63], v[84:87]
	v_mfma_f32_16x16x32_bf16 v[88:91], v[120:123], v[92:95], v[88:91]
	v_mfma_f32_16x16x32_bf16 v[18:21], v[128:131], v[60:63], v[18:21]
	v_mfma_f32_16x16x32_bf16 v[22:25], v[128:131], v[92:95], v[22:25]
	s_setprio 0
	s_barrier
	s_mov_b32 m0, s52
	v_lshl_add_u64 v[132:133], v[132:133], 0, s[12:13]
	ds_read_b128 v[56:59], v17
	ds_read_b128 v[60:63], v17 offset:1024
	ds_read_b128 v[64:67], v17 offset:2048
	ds_read_b128 v[92:95], v17 offset:3072
	global_load_lds_dwordx4 v[132:133], off
	v_lshl_add_u64 v[132:133], v[134:135], 0, s[12:13]
	s_mov_b32 m0, s53
	s_nop 0
	global_load_lds_dwordx4 v[132:133], off
	s_barrier
	s_waitcnt lgkmcnt(0)
	s_setprio 1
	s_waitcnt lgkmcnt(0)
	v_mfma_f32_16x16x32_bf16 v[100:103], v[96:99], v[56:59], v[100:103]
	v_mfma_f32_16x16x32_bf16 v[36:39], v[96:99], v[64:67], v[36:39]
	v_mfma_f32_16x16x32_bf16 v[40:43], v[108:111], v[56:59], v[40:43]
	v_mfma_f32_16x16x32_bf16 v[44:47], v[108:111], v[64:67], v[44:47]
	v_mfma_f32_16x16x32_bf16 v[48:51], v[116:119], v[56:59], v[48:51]
	v_mfma_f32_16x16x32_bf16 v[52:55], v[116:119], v[64:67], v[52:55]
	v_mfma_f32_16x16x32_bf16 v[26:29], v[124:127], v[56:59], v[26:29]
	v_mfma_f32_16x16x32_bf16 v[30:33], v[124:127], v[64:67], v[30:33]
	v_mfma_f32_16x16x32_bf16 v[100:103], v[104:107], v[60:63], v[100:103]
	v_mfma_f32_16x16x32_bf16 v[36:39], v[104:107], v[92:95], v[36:39]
	v_mfma_f32_16x16x32_bf16 v[40:43], v[112:115], v[60:63], v[40:43]
	v_mfma_f32_16x16x32_bf16 v[44:47], v[112:115], v[92:95], v[44:47]
	v_mfma_f32_16x16x32_bf16 v[48:51], v[120:123], v[60:63], v[48:51]
	v_mfma_f32_16x16x32_bf16 v[52:55], v[120:123], v[92:95], v[52:55]
	v_mfma_f32_16x16x32_bf16 v[26:29], v[128:131], v[60:63], v[26:29]
	v_mfma_f32_16x16x32_bf16 v[30:33], v[128:131], v[92:95], v[30:33]
	s_setprio 0
	s_mov_b32 m0, s40
	v_lshl_add_u64 v[56:57], v[140:141], 0, s[12:13]
	s_barrier
	global_load_lds_dwordx4 v[56:57], off
	v_lshl_add_u64 v[56:57], v[142:143], 0, s[12:13]
	s_mov_b32 m0, s41
	s_nop 0
	global_load_lds_dwordx4 v[56:57], off
	s_barrier
	s_waitcnt lgkmcnt(0)
	s_setprio 1
	s_setprio 0
	s_barrier
	s_add_u32 s22, s22, 0x80180
	s_addc_u32 s23, s23, 0
	s_mov_b32 m0, s54
	v_lshl_add_u64 v[56:57], s[22:23], 0, v[136:137]
	global_load_lds_dwordx4 v[56:57], off
	v_lshl_add_u64 v[56:57], s[22:23], 0, v[138:139]
	s_mov_b32 m0, s55
	s_nop 0
	global_load_lds_dwordx4 v[56:57], off
	s_waitcnt vmcnt(6)
	s_barrier
	s_setprio 1
	s_setprio 0
	s_barrier
	ds_read_b128 v[56:59], v13
	ds_read_b128 v[60:63], v13 offset:1024
	ds_read_b128 v[64:67], v13 offset:2048
	ds_read_b128 v[92:95], v13 offset:3072
	s_add_u32 s20, s20, 0x80180
	s_addc_u32 s21, s21, 0
	s_mov_b32 m0, s44
	v_lshl_add_u64 v[132:133], s[20:21], 0, v[136:137]
	ds_read_b128 v[96:99], v14
	ds_read_b128 v[104:107], v14 offset:1024
	ds_read_b128 v[108:111], v14 offset:2048
	ds_read_b128 v[112:115], v14 offset:3072
	ds_read_b128 v[116:119], v14 offset:4096
	ds_read_b128 v[120:123], v14 offset:5120
	ds_read_b128 v[124:127], v14 offset:6144
	ds_read_b128 v[128:131], v14 offset:7168
	global_load_lds_dwordx4 v[132:133], off
	v_lshl_add_u64 v[132:133], s[20:21], 0, v[138:139]
	s_mov_b32 m0, s45
	s_nop 0
	global_load_lds_dwordx4 v[132:133], off
	s_waitcnt lgkmcnt(8)
	s_barrier
	s_waitcnt lgkmcnt(0)
	s_setprio 1
	s_waitcnt lgkmcnt(0)
	v_mfma_f32_16x16x32_bf16 v[68:71], v[96:99], v[56:59], v[68:71]
	v_mfma_f32_16x16x32_bf16 v[72:75], v[96:99], v[64:67], v[72:75]
	v_mfma_f32_16x16x32_bf16 v[76:79], v[108:111], v[56:59], v[76:79]
	v_mfma_f32_16x16x32_bf16 v[80:83], v[108:111], v[64:67], v[80:83]
	v_mfma_f32_16x16x32_bf16 v[84:87], v[116:119], v[56:59], v[84:87]
	v_mfma_f32_16x16x32_bf16 v[88:91], v[116:119], v[64:67], v[88:91]
	v_mfma_f32_16x16x32_bf16 v[18:21], v[124:127], v[56:59], v[18:21]
	v_mfma_f32_16x16x32_bf16 v[22:25], v[124:127], v[64:67], v[22:25]
	v_mfma_f32_16x16x32_bf16 v[68:71], v[104:107], v[60:63], v[68:71]
	v_mfma_f32_16x16x32_bf16 v[72:75], v[104:107], v[92:95], v[72:75]
	v_mfma_f32_16x16x32_bf16 v[76:79], v[112:115], v[60:63], v[76:79]
	v_mfma_f32_16x16x32_bf16 v[80:83], v[112:115], v[92:95], v[80:83]
	v_mfma_f32_16x16x32_bf16 v[84:87], v[120:123], v[60:63], v[84:87]
	v_mfma_f32_16x16x32_bf16 v[88:91], v[120:123], v[92:95], v[88:91]
	v_mfma_f32_16x16x32_bf16 v[18:21], v[128:131], v[60:63], v[18:21]
	v_mfma_f32_16x16x32_bf16 v[22:25], v[128:131], v[92:95], v[22:25]
	s_setprio 0
	s_barrier
	s_mov_b32 m0, s46
	v_lshl_add_u64 v[132:133], s[18:19], 0, v[136:137]
	ds_read_b128 v[56:59], v15
	ds_read_b128 v[60:63], v15 offset:1024
	ds_read_b128 v[64:67], v15 offset:2048
	ds_read_b128 v[92:95], v15 offset:3072
	global_load_lds_dwordx4 v[132:133], off
	v_lshl_add_u64 v[134:135], s[18:19], 0, v[138:139]
	s_mov_b32 m0, s47
	s_nop 0
	global_load_lds_dwordx4 v[134:135], off
	s_barrier
	s_waitcnt lgkmcnt(0)
	s_setprio 1
	s_waitcnt lgkmcnt(0)
	v_mfma_f32_16x16x32_bf16 v[100:103], v[96:99], v[56:59], v[100:103]
	v_mfma_f32_16x16x32_bf16 v[36:39], v[96:99], v[64:67], v[36:39]
	v_mfma_f32_16x16x32_bf16 v[40:43], v[108:111], v[56:59], v[40:43]
	v_mfma_f32_16x16x32_bf16 v[44:47], v[108:111], v[64:67], v[44:47]
	v_mfma_f32_16x16x32_bf16 v[48:51], v[116:119], v[56:59], v[48:51]
	v_mfma_f32_16x16x32_bf16 v[52:55], v[116:119], v[64:67], v[52:55]
	v_mfma_f32_16x16x32_bf16 v[26:29], v[124:127], v[56:59], v[26:29]
	v_mfma_f32_16x16x32_bf16 v[30:33], v[124:127], v[64:67], v[30:33]
	v_mfma_f32_16x16x32_bf16 v[100:103], v[104:107], v[60:63], v[100:103]
	v_mfma_f32_16x16x32_bf16 v[36:39], v[104:107], v[92:95], v[36:39]
	v_mfma_f32_16x16x32_bf16 v[40:43], v[112:115], v[60:63], v[40:43]
	v_mfma_f32_16x16x32_bf16 v[44:47], v[112:115], v[92:95], v[44:47]
	v_mfma_f32_16x16x32_bf16 v[48:51], v[120:123], v[60:63], v[48:51]
	v_mfma_f32_16x16x32_bf16 v[52:55], v[120:123], v[92:95], v[52:55]
	v_mfma_f32_16x16x32_bf16 v[26:29], v[128:131], v[60:63], v[26:29]
	v_mfma_f32_16x16x32_bf16 v[30:33], v[128:131], v[92:95], v[30:33]
	s_setprio 0
	s_mov_b32 m0, s26
	v_lshl_add_u64 v[140:141], s[24:25], 0, v[136:137]
	s_barrier
	global_load_lds_dwordx4 v[140:141], off
	v_lshl_add_u64 v[142:143], s[24:25], 0, v[138:139]
	s_mov_b32 m0, s30
	s_nop 0
	global_load_lds_dwordx4 v[142:143], off
	s_barrier
	s_waitcnt lgkmcnt(0)
	s_setprio 1
	s_setprio 0
	s_barrier
	s_add_u32 s20, s18, 0x80000
	s_addc_u32 s21, s19, 0
	s_mov_b32 m0, s48
	v_lshl_add_u64 v[56:57], s[20:21], 0, v[136:137]
	global_load_lds_dwordx4 v[56:57], off
	v_lshl_add_u64 v[56:57], s[20:21], 0, v[138:139]
	s_mov_b32 m0, s49
	s_nop 0
	global_load_lds_dwordx4 v[56:57], off
	s_waitcnt vmcnt(6)
	s_barrier
	s_setprio 1
	s_setprio 0
	s_barrier
	ds_read_b128 v[56:59], v16
	ds_read_b128 v[60:63], v16 offset:1024
	ds_read_b128 v[64:67], v16 offset:2048
	ds_read_b128 v[92:95], v16 offset:3072
	s_add_u32 s20, s24, 0x80000
	s_addc_u32 s21, s25, 0
	s_mov_b32 m0, s31
	v_lshl_add_u64 v[144:145], s[20:21], 0, v[136:137]
	ds_read_b128 v[96:99], v14 offset:32768
	ds_read_b128 v[104:107], v14 offset:33792
	ds_read_b128 v[108:111], v14 offset:34816
	ds_read_b128 v[112:115], v14 offset:35840
	ds_read_b128 v[116:119], v14 offset:36864
	ds_read_b128 v[120:123], v14 offset:37888
	ds_read_b128 v[124:127], v14 offset:38912
	ds_read_b128 v[128:131], v14 offset:39936
	global_load_lds_dwordx4 v[144:145], off
	v_lshl_add_u64 v[144:145], s[20:21], 0, v[138:139]
	s_mov_b32 m0, s33
	s_nop 0
	global_load_lds_dwordx4 v[144:145], off
	s_waitcnt lgkmcnt(8)
	s_barrier
	s_waitcnt lgkmcnt(0)
	s_setprio 1
	s_waitcnt lgkmcnt(0)
	v_mfma_f32_16x16x32_bf16 v[68:71], v[96:99], v[56:59], v[68:71]
	v_mfma_f32_16x16x32_bf16 v[72:75], v[96:99], v[64:67], v[72:75]
	v_mfma_f32_16x16x32_bf16 v[76:79], v[108:111], v[56:59], v[76:79]
	v_mfma_f32_16x16x32_bf16 v[80:83], v[108:111], v[64:67], v[80:83]
	v_mfma_f32_16x16x32_bf16 v[84:87], v[116:119], v[56:59], v[84:87]
	v_mfma_f32_16x16x32_bf16 v[88:91], v[116:119], v[64:67], v[88:91]
	v_mfma_f32_16x16x32_bf16 v[18:21], v[124:127], v[56:59], v[18:21]
	v_mfma_f32_16x16x32_bf16 v[22:25], v[124:127], v[64:67], v[22:25]
	v_mfma_f32_16x16x32_bf16 v[68:71], v[104:107], v[60:63], v[68:71]
	v_mfma_f32_16x16x32_bf16 v[72:75], v[104:107], v[92:95], v[72:75]
	v_mfma_f32_16x16x32_bf16 v[76:79], v[112:115], v[60:63], v[76:79]
	v_mfma_f32_16x16x32_bf16 v[80:83], v[112:115], v[92:95], v[80:83]
	v_mfma_f32_16x16x32_bf16 v[84:87], v[120:123], v[60:63], v[84:87]
	v_mfma_f32_16x16x32_bf16 v[88:91], v[120:123], v[92:95], v[88:91]
	v_mfma_f32_16x16x32_bf16 v[18:21], v[128:131], v[60:63], v[18:21]
	v_mfma_f32_16x16x32_bf16 v[22:25], v[128:131], v[92:95], v[22:25]
	s_setprio 0
	s_barrier
	s_mov_b32 m0, s52
	v_lshl_add_u64 v[132:133], v[132:133], 0, s[8:9]
	ds_read_b128 v[56:59], v17
	ds_read_b128 v[60:63], v17 offset:1024
	ds_read_b128 v[64:67], v17 offset:2048
	ds_read_b128 v[92:95], v17 offset:3072
	global_load_lds_dwordx4 v[132:133], off
	v_lshl_add_u64 v[132:133], v[134:135], 0, s[8:9]
	s_mov_b32 m0, s53
	s_nop 0
	global_load_lds_dwordx4 v[132:133], off
	s_barrier
	s_waitcnt lgkmcnt(0)
	s_setprio 1
	s_waitcnt lgkmcnt(0)
	v_mfma_f32_16x16x32_bf16 v[100:103], v[96:99], v[56:59], v[100:103]
	v_mfma_f32_16x16x32_bf16 v[36:39], v[96:99], v[64:67], v[36:39]
	v_mfma_f32_16x16x32_bf16 v[40:43], v[108:111], v[56:59], v[40:43]
	v_mfma_f32_16x16x32_bf16 v[44:47], v[108:111], v[64:67], v[44:47]
	v_mfma_f32_16x16x32_bf16 v[48:51], v[116:119], v[56:59], v[48:51]
	v_mfma_f32_16x16x32_bf16 v[52:55], v[116:119], v[64:67], v[52:55]
	v_mfma_f32_16x16x32_bf16 v[26:29], v[124:127], v[56:59], v[26:29]
	v_mfma_f32_16x16x32_bf16 v[30:33], v[124:127], v[64:67], v[30:33]
	v_mfma_f32_16x16x32_bf16 v[100:103], v[104:107], v[60:63], v[100:103]
	v_mfma_f32_16x16x32_bf16 v[36:39], v[104:107], v[92:95], v[36:39]
	v_mfma_f32_16x16x32_bf16 v[40:43], v[112:115], v[60:63], v[40:43]
	v_mfma_f32_16x16x32_bf16 v[44:47], v[112:115], v[92:95], v[44:47]
	v_mfma_f32_16x16x32_bf16 v[48:51], v[120:123], v[60:63], v[48:51]
	v_mfma_f32_16x16x32_bf16 v[52:55], v[120:123], v[92:95], v[52:55]
	v_mfma_f32_16x16x32_bf16 v[26:29], v[128:131], v[60:63], v[26:29]
	v_mfma_f32_16x16x32_bf16 v[30:33], v[128:131], v[92:95], v[30:33]
	s_setprio 0
	s_mov_b32 m0, s40
	v_lshl_add_u64 v[56:57], v[140:141], 0, s[8:9]
	s_barrier
	global_load_lds_dwordx4 v[56:57], off
	v_lshl_add_u64 v[56:57], v[142:143], 0, s[8:9]
	s_mov_b32 m0, s41
	s_nop 0
	global_load_lds_dwordx4 v[56:57], off
	s_barrier
	s_waitcnt lgkmcnt(0)
	s_setprio 1
	s_setprio 0
	s_barrier
	s_add_u32 s18, s18, 0x80080
	s_addc_u32 s19, s19, 0
	s_mov_b32 m0, s54
	v_lshl_add_u64 v[56:57], s[18:19], 0, v[136:137]
	global_load_lds_dwordx4 v[56:57], off
	v_lshl_add_u64 v[56:57], s[18:19], 0, v[138:139]
	s_mov_b32 m0, s55
	s_nop 0
	global_load_lds_dwordx4 v[56:57], off
	s_waitcnt vmcnt(6)
	s_barrier
	s_setprio 1
	s_setprio 0
	v_lshl_or_b32 v2, s59, 8, v12
	v_lshlrev_b64 v[56:57], 2, v[2:3]
	v_lshl_add_u64 v[58:59], v[4:5], 0, v[56:57]
	s_barrier
	v_mov_b32_e32 v62, 0x2000
	v_mov_b32_e32 v63, 0
	v_mov_b32_e32 v56, 0x1a000
	v_mov_b32_e32 v57, 0
	v_mbcnt_lo_u32_b32 v60, -1, 0
	v_mbcnt_hi_u32_b32 v60, -1, v60
	v_and_b32_e32 v61, 15, v60
	v_lshrrev_b32_e32 v60, 4, v60
	v_lshlrev_b32_e32 v60, 2, v60
	v_sub_u32_e32 v60, v60, v61
	v_mul_i32_i24_e32 v60, 0x1ffc, v60
	v_ashrrev_i32_e32 v61, 31, v60
	v_lshl_add_u64 v[58:59], v[60:61], 0, v[58:59]
	global_atomic_add_f32 v[58:59], v68, off
	global_atomic_add_f32 v[58:59], v72, off offset:64
	global_atomic_add_f32 v[58:59], v100, off offset:512
	global_atomic_add_f32 v[58:59], v36, off offset:576
	v_lshl_add_u64 v[60:61], v[58:59], 0, v[62:63]
	global_atomic_add_f32 v[60:61], v69, off
	global_atomic_add_f32 v[60:61], v73, off offset:64
	global_atomic_add_f32 v[60:61], v101, off offset:512
	global_atomic_add_f32 v[60:61], v37, off offset:576
	v_lshl_add_u64 v[58:59], v[60:61], 0, v[62:63]
	global_atomic_add_f32 v[58:59], v70, off
	global_atomic_add_f32 v[58:59], v74, off offset:64
	global_atomic_add_f32 v[58:59], v102, off offset:512
	global_atomic_add_f32 v[58:59], v38, off offset:576
	v_lshl_add_u64 v[60:61], v[58:59], 0, v[62:63]
	global_atomic_add_f32 v[60:61], v71, off
	global_atomic_add_f32 v[60:61], v75, off offset:64
	global_atomic_add_f32 v[60:61], v103, off offset:512
	global_atomic_add_f32 v[60:61], v39, off offset:576
	v_lshl_add_u64 v[58:59], v[60:61], 0, v[56:57]
	global_atomic_add_f32 v[58:59], v76, off
	global_atomic_add_f32 v[58:59], v80, off offset:64
	global_atomic_add_f32 v[58:59], v40, off offset:512
	global_atomic_add_f32 v[58:59], v44, off offset:576
	v_lshl_add_u64 v[60:61], v[58:59], 0, v[62:63]
	global_atomic_add_f32 v[60:61], v77, off
	global_atomic_add_f32 v[60:61], v81, off offset:64
	global_atomic_add_f32 v[60:61], v41, off offset:512
	global_atomic_add_f32 v[60:61], v45, off offset:576
	v_lshl_add_u64 v[58:59], v[60:61], 0, v[62:63]
	global_atomic_add_f32 v[58:59], v78, off
	global_atomic_add_f32 v[58:59], v82, off offset:64
	global_atomic_add_f32 v[58:59], v42, off offset:512
	global_atomic_add_f32 v[58:59], v46, off offset:576
	v_lshl_add_u64 v[60:61], v[58:59], 0, v[62:63]
	global_atomic_add_f32 v[60:61], v79, off
	global_atomic_add_f32 v[60:61], v83, off offset:64
	global_atomic_add_f32 v[60:61], v43, off offset:512
	global_atomic_add_f32 v[60:61], v47, off offset:576
	v_lshl_add_u64 v[58:59], v[60:61], 0, v[56:57]
	global_atomic_add_f32 v[58:59], v84, off
	global_atomic_add_f32 v[58:59], v88, off offset:64
	global_atomic_add_f32 v[58:59], v48, off offset:512
	global_atomic_add_f32 v[58:59], v52, off offset:576
	v_lshl_add_u64 v[60:61], v[58:59], 0, v[62:63]
	global_atomic_add_f32 v[60:61], v85, off
	global_atomic_add_f32 v[60:61], v89, off offset:64
	global_atomic_add_f32 v[60:61], v49, off offset:512
	global_atomic_add_f32 v[60:61], v53, off offset:576
	v_lshl_add_u64 v[58:59], v[60:61], 0, v[62:63]
	global_atomic_add_f32 v[58:59], v86, off
	global_atomic_add_f32 v[58:59], v90, off offset:64
	global_atomic_add_f32 v[58:59], v50, off offset:512
	global_atomic_add_f32 v[58:59], v54, off offset:576
	v_lshl_add_u64 v[60:61], v[58:59], 0, v[62:63]
	global_atomic_add_f32 v[60:61], v87, off
	global_atomic_add_f32 v[60:61], v91, off offset:64
	global_atomic_add_f32 v[60:61], v51, off offset:512
	global_atomic_add_f32 v[60:61], v55, off offset:576
	v_lshl_add_u64 v[58:59], v[60:61], 0, v[56:57]
	global_atomic_add_f32 v[58:59], v18, off
	global_atomic_add_f32 v[58:59], v22, off offset:64
	global_atomic_add_f32 v[58:59], v26, off offset:512
	global_atomic_add_f32 v[58:59], v30, off offset:576
	v_lshl_add_u64 v[60:61], v[58:59], 0, v[62:63]
	global_atomic_add_f32 v[60:61], v19, off
	global_atomic_add_f32 v[60:61], v23, off offset:64
	global_atomic_add_f32 v[60:61], v27, off offset:512
	global_atomic_add_f32 v[60:61], v31, off offset:576
	v_lshl_add_u64 v[58:59], v[60:61], 0, v[62:63]
	global_atomic_add_f32 v[58:59], v20, off
	global_atomic_add_f32 v[58:59], v24, off offset:64
	global_atomic_add_f32 v[58:59], v28, off offset:512
	global_atomic_add_f32 v[58:59], v32, off offset:576
	v_lshl_add_u64 v[60:61], v[58:59], 0, v[62:63]
	global_atomic_add_f32 v[60:61], v21, off
	global_atomic_add_f32 v[60:61], v25, off offset:64
	global_atomic_add_f32 v[60:61], v29, off offset:512
	global_atomic_add_f32 v[60:61], v33, off offset:576
	s_add_i32 s42, s42, s43
	s_mov_b32 s59, s57
	s_mov_b32 s18, s58
	s_mov_b64 s[22:23], s[14:15]
	s_mov_b64 s[20:21], s[16:17]
	s_cbranch_vccnz .LBB0_2012
	s_waitcnt vmcnt(0)
	s_cmpk_gt_u32 s2, 0xff
	s_cbranch_scc1 .LBB0_2015
	s_barrier

.LBB0_2016:
	s_sub_u32 s98, s28, 32
	v_readfirstlane_b32 s2, v34
	s_cmp_lt_u32 s98, 32
	s_cbranch_scc0 .LBB0_2024
	s_lshl_b32 s1, s98, 5
	s_and_b32 s10, s1, 0xffffff00
	s_lshr_b32 s0, s2, 6
	s_ashr_i32 s11, s10, 31
	s_lshr_b32 s8, s2, 8
	s_lshl_b32 s12, s0, 10
	s_lshl_b64 s[10:11], s[10:11], 1
	s_add_u32 s1, s10, 0x800
	s_addc_u32 s9, s11, 0
	s_lshl_b32 s10, s5, 20
	s_add_u32 s10, s3, s10
	s_addc_u32 s11, s4, 0
	s_add_u32 s20, s10, s1
	s_addc_u32 s21, s11, s9
	s_add_i32 s24, s12, 0
	s_add_i32 m0, s24, 0x10000
	v_mov_b32_e32 v3, 0
	global_load_lds_dwordx4 v136, s[20:21]
	s_add_i32 m0, s24, 0x12000
	s_add_u32 s25, s34, 0xd222200
	s_addc_u32 s26, s35, 0
	s_add_u32 s18, s25, s1
	global_load_lds_dwordx4 v138, s[20:21]
	s_addc_u32 s19, s26, s9
	s_mov_b32 m0, s24
	s_add_i32 s27, s24, 0x2000
	global_load_lds_dwordx4 v136, s[18:19]
	s_mov_b32 m0, s27
	s_add_u32 s10, s20, 0x80000
	global_load_lds_dwordx4 v138, s[18:19]
	s_addc_u32 s11, s21, 0
	s_add_i32 m0, s24, 0x14000
	v_mov_b32_e32 v137, v3
	global_load_lds_dwordx4 v136, s[10:11]
	s_add_i32 m0, s24, 0x16000
	v_mov_b32_e32 v139, v3
	global_load_lds_dwordx4 v138, s[10:11]
	s_add_u32 s10, s18, 0x80000
	s_addc_u32 s11, s19, 0
	s_add_i32 s29, s24, 0x4000
	s_mov_b32 m0, s29
	s_add_i32 s30, s24, 0x6000
	global_load_lds_dwordx4 v136, s[10:11]
	s_mov_b32 m0, s30
	v_lshl_add_u64 v[10:11], s[20:21], 0, v[136:137]
	global_load_lds_dwordx4 v138, s[10:11]
	v_lshl_add_u64 v[8:9], s[20:21], 0, v[138:139]
	v_lshl_add_u64 v[6:7], s[18:19], 0, v[136:137]
	s_cmp_lg_u32 s8, 1
	v_lshl_add_u64 v[4:5], s[18:19], 0, v[138:139]
	s_cbranch_scc1 .LBB0_2019
	s_barrier
.LBB0_2019:
	s_add_u32 s10, s34, 0x1eca2200
	s_addc_u32 s11, s35, 0
	s_lshl_b32 s0, s0, 5
	s_and_b32 s13, s0, 0x60
	s_mov_b64 s[0:1], 0x80
	s_add_i32 m0, s24, 0x18000
	v_lshl_add_u64 v[10:11], v[10:11], 0, s[0:1]
	s_lshl_b32 s9, s8, 13
	s_waitcnt vmcnt(4)
	s_barrier
	global_load_lds_dwordx4 v[10:11], off
	v_lshl_add_u64 v[8:9], v[8:9], 0, s[0:1]
	s_add_i32 m0, s24, 0x1a000
	s_add_i32 s31, s24, 0x8000
	s_add_i32 s33, s24, 0xa000
	global_load_lds_dwordx4 v[8:9], off
	v_lshl_add_u64 v[6:7], v[6:7], 0, s[0:1]
	s_mov_b32 m0, s31
	s_add_u32 s14, s20, 0x80080
	global_load_lds_dwordx4 v[6:7], off
	v_lshl_add_u64 v[4:5], v[4:5], 0, s[0:1]
	s_mov_b32 m0, s33
	s_addc_u32 s15, s21, 0
	global_load_lds_dwordx4 v[4:5], off
	s_add_i32 m0, s24, 0x1c000
	v_lshl_add_u64 v[4:5], s[14:15], 0, v[136:137]
	global_load_lds_dwordx4 v[4:5], off
	v_lshl_add_u64 v[4:5], s[14:15], 0, v[138:139]
	s_add_i32 m0, s24, 0x1e000
	v_lshl_or_b32 v2, s8, 6, v166
	global_load_lds_dwordx4 v[4:5], off
	v_lshlrev_b32_e32 v5, 2, v166
	v_lshl_or_b32 v4, v166, 6, v167
	v_and_b32_e32 v5, 32, v5
	v_bitop3_b32 v14, v4, s9, v5 bitop3:0xde
	v_lshl_or_b32 v17, s13, 7, v35
	s_waitcnt vmcnt(6)
	v_lshlrev_b64 v[4:5], 13, v[2:3]
	v_or_b32_e32 v6, 16, v2
	v_mov_b32_e32 v7, v3
	v_or_b32_e32 v8, 32, v2
	v_mov_b32_e32 v9, v3
	v_or_b32_e32 v2, 48, v2
	s_add_i32 s44, 0, 0x10000
	s_add_i32 s46, 0, 0x14000
	s_add_i32 s48, 0, 0x18000
	s_add_i32 s52, 0, 0x1c000
	v_lshlrev_b64 v[6:7], 13, v[6:7]
	v_lshlrev_b64 v[8:9], 13, v[8:9]
	v_lshlrev_b64 v[10:11], 13, v[2:3]
	s_add_i32 s8, s98, s88
	v_add_u32_e32 v13, s44, v17
	v_add_u32_e32 v15, s46, v17
	s_add_i32 s44, s44, s12
	s_add_i32 s46, s46, s12
	v_add_u32_e32 v16, s48, v17
	v_add_u32_e32 v17, s52, v17
	s_add_i32 s48, s48, s12
	s_add_i32 s52, s52, s12
	v_lshl_add_u64 v[4:5], s[10:11], 0, v[4:5]
	v_lshl_add_u64 v[6:7], s[10:11], 0, v[6:7]
	v_lshl_add_u64 v[8:9], s[10:11], 0, v[8:9]
	v_lshl_add_u64 v[10:11], s[10:11], 0, v[10:11]
	v_lshl_or_b32 v12, v1, 2, s13
	s_lshl_b32 s40, s8, 5
	s_lshl_b32 s41, s88, 5
	v_add_u32_e32 v14, 0, v14
	s_add_i32 s42, s24, 0xc000
	s_add_i32 s43, s24, 0xe000
	s_mov_b64 s[8:9], 0x100
	s_add_i32 s45, s44, 0x2000
	s_add_i32 s47, s46, 0x2000
	s_mov_b64 s[10:11], 0x180
	s_add_i32 s49, s48, 0x2000
	s_add_i32 s53, s52, 0x2000
	s_mov_b32 s54, s98
	s_barrier
.LBB0_2020:
	s_add_i32 s54, s88, s54
	s_and_b32 s56, s40, 0xffffff00
	s_and_b32 s55, s54, 7
	s_addk_i32 s56, 0x400
	s_cmp_lt_i32 s54, 32
	s_cselect_b64 s[12:13], -1, 0
	s_and_b64 s[12:13], s[12:13], exec
	s_cselect_b32 s12, s56, s16
	s_ashr_i32 s13, s12, 31
	s_lshl_b64 s[14:15], s[12:13], 1
	s_lshl_b32 s12, s55, 20
	s_add_u32 s12, s3, s12
	s_addc_u32 s13, s4, 0
	s_add_u32 s12, s12, s14
	s_addc_u32 s13, s13, s15
	s_cmp_lt_i32 s54, 32
	s_cselect_b64 s[16:17], -1, 0
	ds_read_b128 v[18:21], v13
	ds_read_b128 v[22:25], v13 offset:1024
	ds_read_b128 v[26:29], v13 offset:2048
	ds_read_b128 v[30:33], v13 offset:3072
	s_and_b64 s[16:17], s[16:17], exec
	s_cselect_b32 s17, s13, s21
	s_cselect_b32 s16, s12, s20
	s_add_u32 s14, s25, s14
	s_addc_u32 s15, s26, s15
	s_cmp_lt_i32 s54, 32
	s_cselect_b64 s[22:23], -1, 0
	s_and_b64 vcc, s[22:23], exec
	s_cselect_b32 s23, s15, s19
	s_cselect_b32 s22, s14, s18
	s_add_u32 s58, s18, 0x80080
	s_addc_u32 s59, s19, 0
	s_mov_b32 m0, s42
	v_lshl_add_u64 v[68:69], s[58:59], 0, v[136:137]
	ds_read_b128 v[36:39], v14
	ds_read_b128 v[40:43], v14 offset:1024
	ds_read_b128 v[44:47], v14 offset:2048
	ds_read_b128 v[48:51], v14 offset:3072
	ds_read_b128 v[52:55], v14 offset:4096
	ds_read_b128 v[56:59], v14 offset:5120
	ds_read_b128 v[60:63], v14 offset:6144
	ds_read_b128 v[64:67], v14 offset:7168
	global_load_lds_dwordx4 v[68:69], off
	v_lshl_add_u64 v[68:69], s[58:59], 0, v[138:139]
	s_mov_b32 m0, s43
	s_nop 0
	global_load_lds_dwordx4 v[68:69], off
	s_waitcnt lgkmcnt(8)
	s_barrier
	s_waitcnt lgkmcnt(0)
	s_setprio 1
	s_waitcnt lgkmcnt(0)
	v_mfma_f32_16x16x32_bf16 v[68:71], v[36:39], v[18:21], 0
	v_mfma_f32_16x16x32_bf16 v[76:79], v[44:47], v[18:21], 0
	v_mfma_f32_16x16x32_bf16 v[84:87], v[52:55], v[18:21], 0
	v_mfma_f32_16x16x32_bf16 v[18:21], v[60:63], v[18:21], 0
	v_mfma_f32_16x16x32_bf16 v[68:71], v[40:43], v[22:25], v[68:71]
	v_mfma_f32_16x16x32_bf16 v[72:75], v[36:39], v[26:29], 0
	v_mfma_f32_16x16x32_bf16 v[76:79], v[48:51], v[22:25], v[76:79]
	v_mfma_f32_16x16x32_bf16 v[80:83], v[44:47], v[26:29], 0
	v_mfma_f32_16x16x32_bf16 v[84:87], v[56:59], v[22:25], v[84:87]
	v_mfma_f32_16x16x32_bf16 v[88:91], v[52:55], v[26:29], 0
	v_mfma_f32_16x16x32_bf16 v[18:21], v[64:67], v[22:25], v[18:21]
	v_mfma_f32_16x16x32_bf16 v[22:25], v[60:63], v[26:29], 0
	v_mfma_f32_16x16x32_bf16 v[72:75], v[40:43], v[30:33], v[72:75]
	v_mfma_f32_16x16x32_bf16 v[80:83], v[48:51], v[30:33], v[80:83]
	v_mfma_f32_16x16x32_bf16 v[88:91], v[56:59], v[30:33], v[88:91]
	v_mfma_f32_16x16x32_bf16 v[22:25], v[64:67], v[30:33], v[22:25]
	s_setprio 0
	s_barrier
	v_lshl_add_u64 v[132:133], s[20:21], 0, v[136:137]
	s_mov_b32 m0, s44
	v_lshl_add_u64 v[100:101], v[132:133], 0, s[8:9]
	v_lshl_add_u64 v[134:135], s[20:21], 0, v[138:139]
	ds_read_b128 v[26:29], v15
	ds_read_b128 v[30:33], v15 offset:1024
	ds_read_b128 v[92:95], v15 offset:2048
	ds_read_b128 v[96:99], v15 offset:3072
	global_load_lds_dwordx4 v[100:101], off
	v_lshl_add_u64 v[100:101], v[134:135], 0, s[8:9]
	s_mov_b32 m0, s45
	s_nop 0
	global_load_lds_dwordx4 v[100:101], off
	s_barrier
	s_waitcnt lgkmcnt(0)
	s_setprio 1
	s_waitcnt lgkmcnt(0)
	v_mfma_f32_16x16x32_bf16 v[100:103], v[36:39], v[26:29], 0
	v_mfma_f32_16x16x32_bf16 v[36:39], v[36:39], v[92:95], 0
	v_mfma_f32_16x16x32_bf16 v[100:103], v[40:43], v[30:33], v[100:103]
	v_mfma_f32_16x16x32_bf16 v[36:39], v[40:43], v[96:99], v[36:39]
	v_mfma_f32_16x16x32_bf16 v[40:43], v[44:47], v[26:29], 0
	v_mfma_f32_16x16x32_bf16 v[44:47], v[44:47], v[92:95], 0
	v_mfma_f32_16x16x32_bf16 v[40:43], v[48:51], v[30:33], v[40:43]
	v_mfma_f32_16x16x32_bf16 v[44:47], v[48:51], v[96:99], v[44:47]
	v_mfma_f32_16x16x32_bf16 v[48:51], v[52:55], v[26:29], 0
	v_mfma_f32_16x16x32_bf16 v[26:29], v[60:63], v[26:29], 0
	v_mfma_f32_16x16x32_bf16 v[48:51], v[56:59], v[30:33], v[48:51]
	v_mfma_f32_16x16x32_bf16 v[52:55], v[52:55], v[92:95], 0
	v_mfma_f32_16x16x32_bf16 v[26:29], v[64:67], v[30:33], v[26:29]
	v_mfma_f32_16x16x32_bf16 v[30:33], v[60:63], v[92:95], 0
	v_mfma_f32_16x16x32_bf16 v[52:55], v[56:59], v[96:99], v[52:55]
	v_mfma_f32_16x16x32_bf16 v[30:33], v[64:67], v[96:99], v[30:33]
	s_setprio 0
	v_lshl_add_u64 v[140:141], s[18:19], 0, v[136:137]
	s_mov_b32 m0, s24
	v_lshl_add_u64 v[56:57], v[140:141], 0, s[8:9]
	v_lshl_add_u64 v[142:143], s[18:19], 0, v[138:139]
	s_barrier
	global_load_lds_dwordx4 v[56:57], off
	v_lshl_add_u64 v[56:57], v[142:143], 0, s[8:9]
	s_mov_b32 m0, s27
	s_nop 0
	global_load_lds_dwordx4 v[56:57], off
	s_barrier
	s_waitcnt lgkmcnt(0)
	s_setprio 1
	s_setprio 0
	s_barrier
	s_add_u32 s58, s20, 0x80100
	s_addc_u32 s59, s21, 0
	s_mov_b32 m0, s46
	v_lshl_add_u64 v[56:57], s[58:59], 0, v[136:137]
	global_load_lds_dwordx4 v[56:57], off
	v_lshl_add_u64 v[56:57], s[58:59], 0, v[138:139]
	s_mov_b32 m0, s47
	s_nop 0
	global_load_lds_dwordx4 v[56:57], off
	s_waitcnt vmcnt(6)
	s_barrier
	s_setprio 1
	s_setprio 0
	s_barrier
	ds_read_b128 v[56:59], v16
	ds_read_b128 v[60:63], v16 offset:1024
	ds_read_b128 v[64:67], v16 offset:2048
	ds_read_b128 v[92:95], v16 offset:3072
	s_add_u32 s58, s18, 0x80100
	s_addc_u32 s59, s19, 0
	s_mov_b32 m0, s29
	v_lshl_add_u64 v[144:145], s[58:59], 0, v[136:137]
	ds_read_b128 v[96:99], v14 offset:32768
	ds_read_b128 v[104:107], v14 offset:33792
	ds_read_b128 v[108:111], v14 offset:34816
	ds_read_b128 v[112:115], v14 offset:35840
	ds_read_b128 v[116:119], v14 offset:36864
	ds_read_b128 v[120:123], v14 offset:37888
	ds_read_b128 v[124:127], v14 offset:38912
	ds_read_b128 v[128:131], v14 offset:39936
	global_load_lds_dwordx4 v[144:145], off
	v_lshl_add_u64 v[144:145], s[58:59], 0, v[138:139]
	s_mov_b32 m0, s30
	s_nop 0
	global_load_lds_dwordx4 v[144:145], off
	s_waitcnt lgkmcnt(8)
	s_barrier
	s_waitcnt lgkmcnt(0)
	s_setprio 1
	s_waitcnt lgkmcnt(0)
	v_mfma_f32_16x16x32_bf16 v[68:71], v[96:99], v[56:59], v[68:71]
	v_mfma_f32_16x16x32_bf16 v[72:75], v[96:99], v[64:67], v[72:75]
	v_mfma_f32_16x16x32_bf16 v[76:79], v[108:111], v[56:59], v[76:79]
	v_mfma_f32_16x16x32_bf16 v[80:83], v[108:111], v[64:67], v[80:83]
	v_mfma_f32_16x16x32_bf16 v[84:87], v[116:119], v[56:59], v[84:87]
	v_mfma_f32_16x16x32_bf16 v[88:91], v[116:119], v[64:67], v[88:91]
	v_mfma_f32_16x16x32_bf16 v[18:21], v[124:127], v[56:59], v[18:21]
	v_mfma_f32_16x16x32_bf16 v[22:25], v[124:127], v[64:67], v[22:25]
	v_mfma_f32_16x16x32_bf16 v[68:71], v[104:107], v[60:63], v[68:71]
	v_mfma_f32_16x16x32_bf16 v[72:75], v[104:107], v[92:95], v[72:75]
	v_mfma_f32_16x16x32_bf16 v[76:79], v[112:115], v[60:63], v[76:79]
	v_mfma_f32_16x16x32_bf16 v[80:83], v[112:115], v[92:95], v[80:83]
	v_mfma_f32_16x16x32_bf16 v[84:87], v[120:123], v[60:63], v[84:87]
	v_mfma_f32_16x16x32_bf16 v[88:91], v[120:123], v[92:95], v[88:91]
	v_mfma_f32_16x16x32_bf16 v[18:21], v[128:131], v[60:63], v[18:21]
	v_mfma_f32_16x16x32_bf16 v[22:25], v[128:131], v[92:95], v[22:25]
	s_setprio 0
	s_barrier
	s_mov_b32 m0, s48
	v_lshl_add_u64 v[132:133], v[132:133], 0, s[10:11]
	ds_read_b128 v[56:59], v17
	ds_read_b128 v[60:63], v17 offset:1024
	ds_read_b128 v[64:67], v17 offset:2048
	ds_read_b128 v[92:95], v17 offset:3072
	global_load_lds_dwordx4 v[132:133], off
	v_lshl_add_u64 v[132:133], v[134:135], 0, s[10:11]
	s_mov_b32 m0, s49
	s_nop 0
	global_load_lds_dwordx4 v[132:133], off
	s_barrier
	s_waitcnt lgkmcnt(0)
	s_setprio 1
	s_waitcnt lgkmcnt(0)
	v_mfma_f32_16x16x32_bf16 v[100:103], v[96:99], v[56:59], v[100:103]
	v_mfma_f32_16x16x32_bf16 v[36:39], v[96:99], v[64:67], v[36:39]
	v_mfma_f32_16x16x32_bf16 v[40:43], v[108:111], v[56:59], v[40:43]
	v_mfma_f32_16x16x32_bf16 v[44:47], v[108:111], v[64:67], v[44:47]
	v_mfma_f32_16x16x32_bf16 v[48:51], v[116:119], v[56:59], v[48:51]
	v_mfma_f32_16x16x32_bf16 v[52:55], v[116:119], v[64:67], v[52:55]
	v_mfma_f32_16x16x32_bf16 v[26:29], v[124:127], v[56:59], v[26:29]
	v_mfma_f32_16x16x32_bf16 v[30:33], v[124:127], v[64:67], v[30:33]
	v_mfma_f32_16x16x32_bf16 v[100:103], v[104:107], v[60:63], v[100:103]
	v_mfma_f32_16x16x32_bf16 v[36:39], v[104:107], v[92:95], v[36:39]
	v_mfma_f32_16x16x32_bf16 v[40:43], v[112:115], v[60:63], v[40:43]
	v_mfma_f32_16x16x32_bf16 v[44:47], v[112:115], v[92:95], v[44:47]
	v_mfma_f32_16x16x32_bf16 v[48:51], v[120:123], v[60:63], v[48:51]
	v_mfma_f32_16x16x32_bf16 v[52:55], v[120:123], v[92:95], v[52:55]
	v_mfma_f32_16x16x32_bf16 v[26:29], v[128:131], v[60:63], v[26:29]
	v_mfma_f32_16x16x32_bf16 v[30:33], v[128:131], v[92:95], v[30:33]
	s_setprio 0
	s_mov_b32 m0, s31
	v_lshl_add_u64 v[56:57], v[140:141], 0, s[10:11]
	s_barrier
	global_load_lds_dwordx4 v[56:57], off
	v_lshl_add_u64 v[56:57], v[142:143], 0, s[10:11]
	s_mov_b32 m0, s33
	s_nop 0
	global_load_lds_dwordx4 v[56:57], off
	s_barrier
	s_waitcnt lgkmcnt(0)
	s_setprio 1
	s_setprio 0
	s_barrier
	s_add_u32 s20, s20, 0x80180
	s_addc_u32 s21, s21, 0
	s_mov_b32 m0, s52
	v_lshl_add_u64 v[56:57], s[20:21], 0, v[136:137]
	global_load_lds_dwordx4 v[56:57], off
	v_lshl_add_u64 v[56:57], s[20:21], 0, v[138:139]
	s_mov_b32 m0, s53
	s_nop 0
	global_load_lds_dwordx4 v[56:57], off
	s_waitcnt vmcnt(6)
	s_barrier
	s_setprio 1
	s_setprio 0
	s_barrier
	ds_read_b128 v[56:59], v13
	ds_read_b128 v[60:63], v13 offset:1024
	ds_read_b128 v[64:67], v13 offset:2048
	ds_read_b128 v[92:95], v13 offset:3072
	s_add_u32 s18, s18, 0x80180
	s_addc_u32 s19, s19, 0
	s_mov_b32 m0, s42
	v_lshl_add_u64 v[132:133], s[18:19], 0, v[136:137]
	ds_read_b128 v[96:99], v14
	ds_read_b128 v[104:107], v14 offset:1024
	ds_read_b128 v[108:111], v14 offset:2048
	ds_read_b128 v[112:115], v14 offset:3072
	ds_read_b128 v[116:119], v14 offset:4096
	ds_read_b128 v[120:123], v14 offset:5120
	ds_read_b128 v[124:127], v14 offset:6144
	ds_read_b128 v[128:131], v14 offset:7168
	global_load_lds_dwordx4 v[132:133], off
	v_lshl_add_u64 v[132:133], s[18:19], 0, v[138:139]
	s_mov_b32 m0, s43
	s_nop 0
	global_load_lds_dwordx4 v[132:133], off
	s_waitcnt lgkmcnt(8)
	s_barrier
	s_waitcnt lgkmcnt(0)
	s_setprio 1
	s_waitcnt lgkmcnt(0)
	v_mfma_f32_16x16x32_bf16 v[68:71], v[96:99], v[56:59], v[68:71]
	v_mfma_f32_16x16x32_bf16 v[72:75], v[96:99], v[64:67], v[72:75]
	v_mfma_f32_16x16x32_bf16 v[76:79], v[108:111], v[56:59], v[76:79]
	v_mfma_f32_16x16x32_bf16 v[80:83], v[108:111], v[64:67], v[80:83]
	v_mfma_f32_16x16x32_bf16 v[84:87], v[116:119], v[56:59], v[84:87]
	v_mfma_f32_16x16x32_bf16 v[88:91], v[116:119], v[64:67], v[88:91]
	v_mfma_f32_16x16x32_bf16 v[18:21], v[124:127], v[56:59], v[18:21]
	v_mfma_f32_16x16x32_bf16 v[22:25], v[124:127], v[64:67], v[22:25]
	v_mfma_f32_16x16x32_bf16 v[68:71], v[104:107], v[60:63], v[68:71]
	v_mfma_f32_16x16x32_bf16 v[72:75], v[104:107], v[92:95], v[72:75]
	v_mfma_f32_16x16x32_bf16 v[76:79], v[112:115], v[60:63], v[76:79]
	v_mfma_f32_16x16x32_bf16 v[80:83], v[112:115], v[92:95], v[80:83]
	v_mfma_f32_16x16x32_bf16 v[84:87], v[120:123], v[60:63], v[84:87]
	v_mfma_f32_16x16x32_bf16 v[88:91], v[120:123], v[92:95], v[88:91]
	v_mfma_f32_16x16x32_bf16 v[18:21], v[128:131], v[60:63], v[18:21]
	v_mfma_f32_16x16x32_bf16 v[22:25], v[128:131], v[92:95], v[22:25]
	s_setprio 0
	s_barrier
	s_mov_b32 m0, s44
	v_lshl_add_u64 v[132:133], s[16:17], 0, v[136:137]
	ds_read_b128 v[56:59], v15
	ds_read_b128 v[60:63], v15 offset:1024
	ds_read_b128 v[64:67], v15 offset:2048
	ds_read_b128 v[92:95], v15 offset:3072
	global_load_lds_dwordx4 v[132:133], off
	v_lshl_add_u64 v[134:135], s[16:17], 0, v[138:139]
	s_mov_b32 m0, s45
	s_nop 0
	global_load_lds_dwordx4 v[134:135], off
	s_barrier
	s_waitcnt lgkmcnt(0)
	s_setprio 1
	s_waitcnt lgkmcnt(0)
	v_mfma_f32_16x16x32_bf16 v[100:103], v[96:99], v[56:59], v[100:103]
	v_mfma_f32_16x16x32_bf16 v[36:39], v[96:99], v[64:67], v[36:39]
	v_mfma_f32_16x16x32_bf16 v[40:43], v[108:111], v[56:59], v[40:43]
	v_mfma_f32_16x16x32_bf16 v[44:47], v[108:111], v[64:67], v[44:47]
	v_mfma_f32_16x16x32_bf16 v[48:51], v[116:119], v[56:59], v[48:51]
	v_mfma_f32_16x16x32_bf16 v[52:55], v[116:119], v[64:67], v[52:55]
	v_mfma_f32_16x16x32_bf16 v[26:29], v[124:127], v[56:59], v[26:29]
	v_mfma_f32_16x16x32_bf16 v[30:33], v[124:127], v[64:67], v[30:33]
	v_mfma_f32_16x16x32_bf16 v[100:103], v[104:107], v[60:63], v[100:103]
	v_mfma_f32_16x16x32_bf16 v[36:39], v[104:107], v[92:95], v[36:39]
	v_mfma_f32_16x16x32_bf16 v[40:43], v[112:115], v[60:63], v[40:43]
	v_mfma_f32_16x16x32_bf16 v[44:47], v[112:115], v[92:95], v[44:47]
	v_mfma_f32_16x16x32_bf16 v[48:51], v[120:123], v[60:63], v[48:51]
	v_mfma_f32_16x16x32_bf16 v[52:55], v[120:123], v[92:95], v[52:55]
	v_mfma_f32_16x16x32_bf16 v[26:29], v[128:131], v[60:63], v[26:29]
	v_mfma_f32_16x16x32_bf16 v[30:33], v[128:131], v[92:95], v[30:33]
	s_setprio 0
	s_mov_b32 m0, s24
	v_lshl_add_u64 v[140:141], s[22:23], 0, v[136:137]
	s_barrier
	global_load_lds_dwordx4 v[140:141], off
	v_lshl_add_u64 v[142:143], s[22:23], 0, v[138:139]
	s_mov_b32 m0, s27
	s_nop 0
	global_load_lds_dwordx4 v[142:143], off
	s_barrier
	s_waitcnt lgkmcnt(0)
	s_setprio 1
	s_setprio 0
	s_barrier
	s_add_u32 s18, s16, 0x80000
	s_addc_u32 s19, s17, 0
	s_mov_b32 m0, s46
	v_lshl_add_u64 v[56:57], s[18:19], 0, v[136:137]
	global_load_lds_dwordx4 v[56:57], off
	v_lshl_add_u64 v[56:57], s[18:19], 0, v[138:139]
	s_mov_b32 m0, s47
	s_nop 0
	global_load_lds_dwordx4 v[56:57], off
	s_waitcnt vmcnt(6)
	s_barrier
	s_setprio 1
	s_setprio 0
	s_barrier
	ds_read_b128 v[56:59], v16
	ds_read_b128 v[60:63], v16 offset:1024
	ds_read_b128 v[64:67], v16 offset:2048
	ds_read_b128 v[92:95], v16 offset:3072
	s_add_u32 s18, s22, 0x80000
	s_addc_u32 s19, s23, 0
	s_mov_b32 m0, s29
	v_lshl_add_u64 v[144:145], s[18:19], 0, v[136:137]
	ds_read_b128 v[96:99], v14 offset:32768
	ds_read_b128 v[104:107], v14 offset:33792
	ds_read_b128 v[108:111], v14 offset:34816
	ds_read_b128 v[112:115], v14 offset:35840
	ds_read_b128 v[116:119], v14 offset:36864
	ds_read_b128 v[120:123], v14 offset:37888
	ds_read_b128 v[124:127], v14 offset:38912
	ds_read_b128 v[128:131], v14 offset:39936
	global_load_lds_dwordx4 v[144:145], off
	v_lshl_add_u64 v[144:145], s[18:19], 0, v[138:139]
	s_mov_b32 m0, s30
	s_nop 0
	global_load_lds_dwordx4 v[144:145], off
	s_waitcnt lgkmcnt(8)
	s_barrier
	s_waitcnt lgkmcnt(0)
	s_setprio 1
	s_waitcnt lgkmcnt(0)
	v_mfma_f32_16x16x32_bf16 v[68:71], v[96:99], v[56:59], v[68:71]
	v_mfma_f32_16x16x32_bf16 v[72:75], v[96:99], v[64:67], v[72:75]
	v_mfma_f32_16x16x32_bf16 v[76:79], v[108:111], v[56:59], v[76:79]
	v_mfma_f32_16x16x32_bf16 v[80:83], v[108:111], v[64:67], v[80:83]
	v_mfma_f32_16x16x32_bf16 v[84:87], v[116:119], v[56:59], v[84:87]
	v_mfma_f32_16x16x32_bf16 v[88:91], v[116:119], v[64:67], v[88:91]
	v_mfma_f32_16x16x32_bf16 v[18:21], v[124:127], v[56:59], v[18:21]
	v_mfma_f32_16x16x32_bf16 v[22:25], v[124:127], v[64:67], v[22:25]
	v_mfma_f32_16x16x32_bf16 v[68:71], v[104:107], v[60:63], v[68:71]
	v_mfma_f32_16x16x32_bf16 v[72:75], v[104:107], v[92:95], v[72:75]
	v_mfma_f32_16x16x32_bf16 v[76:79], v[112:115], v[60:63], v[76:79]
	v_mfma_f32_16x16x32_bf16 v[80:83], v[112:115], v[92:95], v[80:83]
	v_mfma_f32_16x16x32_bf16 v[84:87], v[120:123], v[60:63], v[84:87]
	v_mfma_f32_16x16x32_bf16 v[88:91], v[120:123], v[92:95], v[88:91]
	v_mfma_f32_16x16x32_bf16 v[18:21], v[128:131], v[60:63], v[18:21]
	v_mfma_f32_16x16x32_bf16 v[22:25], v[128:131], v[92:95], v[22:25]
	s_setprio 0
	s_barrier
	s_mov_b32 m0, s48
	v_lshl_add_u64 v[132:133], v[132:133], 0, s[0:1]
	ds_read_b128 v[56:59], v17
	ds_read_b128 v[60:63], v17 offset:1024
	ds_read_b128 v[64:67], v17 offset:2048
	ds_read_b128 v[92:95], v17 offset:3072
	global_load_lds_dwordx4 v[132:133], off
	v_lshl_add_u64 v[132:133], v[134:135], 0, s[0:1]
	s_mov_b32 m0, s49
	s_nop 0
	global_load_lds_dwordx4 v[132:133], off
	s_barrier
	s_waitcnt lgkmcnt(0)
	s_setprio 1
	s_waitcnt lgkmcnt(0)
	v_mfma_f32_16x16x32_bf16 v[100:103], v[96:99], v[56:59], v[100:103]
	v_mfma_f32_16x16x32_bf16 v[36:39], v[96:99], v[64:67], v[36:39]
	v_mfma_f32_16x16x32_bf16 v[40:43], v[108:111], v[56:59], v[40:43]
	v_mfma_f32_16x16x32_bf16 v[44:47], v[108:111], v[64:67], v[44:47]
	v_mfma_f32_16x16x32_bf16 v[48:51], v[116:119], v[56:59], v[48:51]
	v_mfma_f32_16x16x32_bf16 v[52:55], v[116:119], v[64:67], v[52:55]
	v_mfma_f32_16x16x32_bf16 v[26:29], v[124:127], v[56:59], v[26:29]
	v_mfma_f32_16x16x32_bf16 v[30:33], v[124:127], v[64:67], v[30:33]
	v_mfma_f32_16x16x32_bf16 v[100:103], v[104:107], v[60:63], v[100:103]
	v_mfma_f32_16x16x32_bf16 v[36:39], v[104:107], v[92:95], v[36:39]
	v_mfma_f32_16x16x32_bf16 v[40:43], v[112:115], v[60:63], v[40:43]
	v_mfma_f32_16x16x32_bf16 v[44:47], v[112:115], v[92:95], v[44:47]
	v_mfma_f32_16x16x32_bf16 v[48:51], v[120:123], v[60:63], v[48:51]
	v_mfma_f32_16x16x32_bf16 v[52:55], v[120:123], v[92:95], v[52:55]
	v_mfma_f32_16x16x32_bf16 v[26:29], v[128:131], v[60:63], v[26:29]
	v_mfma_f32_16x16x32_bf16 v[30:33], v[128:131], v[92:95], v[30:33]
	s_setprio 0
	s_mov_b32 m0, s31
	v_lshl_add_u64 v[56:57], v[140:141], 0, s[0:1]
	s_barrier
	global_load_lds_dwordx4 v[56:57], off
	v_lshl_add_u64 v[56:57], v[142:143], 0, s[0:1]
	s_mov_b32 m0, s33
	s_nop 0
	global_load_lds_dwordx4 v[56:57], off
	s_barrier
	s_waitcnt lgkmcnt(0)
	s_setprio 1
	s_setprio 0
	s_barrier
	s_add_u32 s16, s16, 0x80080
	s_addc_u32 s17, s17, 0
	s_mov_b32 m0, s52
	v_lshl_add_u64 v[56:57], s[16:17], 0, v[136:137]
	global_load_lds_dwordx4 v[56:57], off
	v_lshl_add_u64 v[56:57], s[16:17], 0, v[138:139]
	s_mov_b32 m0, s53
	s_nop 0
	global_load_lds_dwordx4 v[56:57], off
	s_waitcnt vmcnt(6)
	s_barrier
	s_setprio 1
	s_setprio 0
	v_lshl_or_b32 v2, s5, 8, v12
	v_lshlrev_b64 v[56:57], 2, v[2:3]
	v_lshl_add_u64 v[58:59], v[4:5], 0, v[56:57]
	s_barrier
	v_mov_b32_e32 v62, 0x2000
	v_mov_b32_e32 v63, 0
	v_mov_b32_e32 v56, 0x1a000
	v_mov_b32_e32 v57, 0
	v_mbcnt_lo_u32_b32 v60, -1, 0
	v_mbcnt_hi_u32_b32 v60, -1, v60
	v_and_b32_e32 v61, 15, v60
	v_lshrrev_b32_e32 v60, 4, v60
	v_lshlrev_b32_e32 v60, 2, v60
	v_sub_u32_e32 v60, v60, v61
	v_mul_i32_i24_e32 v60, 0x1ffc, v60
	v_ashrrev_i32_e32 v61, 31, v60
	v_lshl_add_u64 v[58:59], v[60:61], 0, v[58:59]
	global_atomic_add_f32 v[58:59], v68, off
	global_atomic_add_f32 v[58:59], v72, off offset:64
	global_atomic_add_f32 v[58:59], v100, off offset:512
	global_atomic_add_f32 v[58:59], v36, off offset:576
	v_lshl_add_u64 v[60:61], v[58:59], 0, v[62:63]
	global_atomic_add_f32 v[60:61], v69, off
	global_atomic_add_f32 v[60:61], v73, off offset:64
	global_atomic_add_f32 v[60:61], v101, off offset:512
	global_atomic_add_f32 v[60:61], v37, off offset:576
	v_lshl_add_u64 v[58:59], v[60:61], 0, v[62:63]
	global_atomic_add_f32 v[58:59], v70, off
	global_atomic_add_f32 v[58:59], v74, off offset:64
	global_atomic_add_f32 v[58:59], v102, off offset:512
	global_atomic_add_f32 v[58:59], v38, off offset:576
	v_lshl_add_u64 v[60:61], v[58:59], 0, v[62:63]
	global_atomic_add_f32 v[60:61], v71, off
	global_atomic_add_f32 v[60:61], v75, off offset:64
	global_atomic_add_f32 v[60:61], v103, off offset:512
	global_atomic_add_f32 v[60:61], v39, off offset:576
	v_lshl_add_u64 v[58:59], v[60:61], 0, v[56:57]
	global_atomic_add_f32 v[58:59], v76, off
	global_atomic_add_f32 v[58:59], v80, off offset:64
	global_atomic_add_f32 v[58:59], v40, off offset:512
	global_atomic_add_f32 v[58:59], v44, off offset:576
	v_lshl_add_u64 v[60:61], v[58:59], 0, v[62:63]
	global_atomic_add_f32 v[60:61], v77, off
	global_atomic_add_f32 v[60:61], v81, off offset:64
	global_atomic_add_f32 v[60:61], v41, off offset:512
	global_atomic_add_f32 v[60:61], v45, off offset:576
	v_lshl_add_u64 v[58:59], v[60:61], 0, v[62:63]
	global_atomic_add_f32 v[58:59], v78, off
	global_atomic_add_f32 v[58:59], v82, off offset:64
	global_atomic_add_f32 v[58:59], v42, off offset:512
	global_atomic_add_f32 v[58:59], v46, off offset:576
	v_lshl_add_u64 v[60:61], v[58:59], 0, v[62:63]
	global_atomic_add_f32 v[60:61], v79, off
	global_atomic_add_f32 v[60:61], v83, off offset:64
	global_atomic_add_f32 v[60:61], v43, off offset:512
	global_atomic_add_f32 v[60:61], v47, off offset:576
	v_lshl_add_u64 v[58:59], v[60:61], 0, v[56:57]
	global_atomic_add_f32 v[58:59], v84, off
	global_atomic_add_f32 v[58:59], v88, off offset:64
	global_atomic_add_f32 v[58:59], v48, off offset:512
	global_atomic_add_f32 v[58:59], v52, off offset:576
	v_lshl_add_u64 v[60:61], v[58:59], 0, v[62:63]
	global_atomic_add_f32 v[60:61], v85, off
	global_atomic_add_f32 v[60:61], v89, off offset:64
	global_atomic_add_f32 v[60:61], v49, off offset:512
	global_atomic_add_f32 v[60:61], v53, off offset:576
	v_lshl_add_u64 v[58:59], v[60:61], 0, v[62:63]
	global_atomic_add_f32 v[58:59], v86, off
	global_atomic_add_f32 v[58:59], v90, off offset:64
	global_atomic_add_f32 v[58:59], v50, off offset:512
	global_atomic_add_f32 v[58:59], v54, off offset:576
	v_lshl_add_u64 v[60:61], v[58:59], 0, v[62:63]
	global_atomic_add_f32 v[60:61], v87, off
	global_atomic_add_f32 v[60:61], v91, off offset:64
	global_atomic_add_f32 v[60:61], v51, off offset:512
	global_atomic_add_f32 v[60:61], v55, off offset:576
	v_lshl_add_u64 v[58:59], v[60:61], 0, v[56:57]
	global_atomic_add_f32 v[58:59], v18, off
	global_atomic_add_f32 v[58:59], v22, off offset:64
	global_atomic_add_f32 v[58:59], v26, off offset:512
	global_atomic_add_f32 v[58:59], v30, off offset:576
	v_lshl_add_u64 v[60:61], v[58:59], 0, v[62:63]
	global_atomic_add_f32 v[60:61], v19, off
	global_atomic_add_f32 v[60:61], v23, off offset:64
	global_atomic_add_f32 v[60:61], v27, off offset:512
	global_atomic_add_f32 v[60:61], v31, off offset:576
	v_lshl_add_u64 v[58:59], v[60:61], 0, v[62:63]
	global_atomic_add_f32 v[58:59], v20, off
	global_atomic_add_f32 v[58:59], v24, off offset:64
	global_atomic_add_f32 v[58:59], v28, off offset:512
	global_atomic_add_f32 v[58:59], v32, off offset:576
	v_lshl_add_u64 v[60:61], v[58:59], 0, v[62:63]
	global_atomic_add_f32 v[60:61], v21, off
	global_atomic_add_f32 v[60:61], v25, off offset:64
	global_atomic_add_f32 v[60:61], v29, off offset:512
	global_atomic_add_f32 v[60:61], v33, off offset:576
	s_add_i32 s40, s40, s41
	s_mov_b32 s5, s55
	s_mov_b32 s16, s56
	s_mov_b64 s[20:21], s[12:13]
	s_mov_b64 s[18:19], s[14:15]
	s_cbranch_vccnz .LBB0_2020
	s_waitcnt vmcnt(0)
	s_cmpk_gt_u32 s2, 0xff
	s_cbranch_scc1 .LBB0_2023
	s_barrier

.LBB0_2174:
	s_add_i32 s48, s88, s48
	s_and_b32 s49, s48, 7
	s_and_b32 s52, s31, 0xffffff00
	s_cmp_lt_i32 s48, 64
	s_cselect_b64 s[10:11], -1, 0
	s_and_b64 s[10:11], s[10:11], exec
	s_cselect_b32 s10, s52, s14
	s_ashr_i32 s11, s10, 31
	s_lshl_b64 s[12:13], s[10:11], 1
	s_lshl_b32 s10, s49, 20
	s_add_u32 s10, s3, s10
	s_addc_u32 s11, s4, 0
	s_add_u32 s10, s10, s12
	s_addc_u32 s11, s11, s13
	s_cmp_lt_i32 s48, 64
	s_cselect_b64 s[14:15], -1, 0
	ds_read_b128 v[18:21], v13
	ds_read_b128 v[22:25], v13 offset:1024
	ds_read_b128 v[26:29], v13 offset:2048
	ds_read_b128 v[30:33], v13 offset:3072
	s_and_b64 s[14:15], s[14:15], exec
	s_cselect_b32 s15, s11, s19
	s_cselect_b32 s14, s10, s18
	s_add_u32 s12, s22, s12
	s_addc_u32 s13, s23, s13
	s_cmp_lt_i32 s48, 64
	s_cselect_b64 s[20:21], -1, 0
	s_and_b64 vcc, s[20:21], exec
	s_cselect_b32 s21, s13, s17
	s_cselect_b32 s20, s12, s16
	s_add_u32 s54, s16, 0x80080
	s_addc_u32 s55, s17, 0
	s_mov_b32 m0, s36
	v_lshl_add_u64 v[68:69], s[54:55], 0, v[132:133]
	ds_read_b128 v[36:39], v14
	ds_read_b128 v[40:43], v14 offset:1024
	ds_read_b128 v[44:47], v14 offset:2048
	ds_read_b128 v[48:51], v14 offset:3072
	ds_read_b128 v[52:55], v14 offset:4096
	ds_read_b128 v[56:59], v14 offset:5120
	ds_read_b128 v[60:63], v14 offset:6144
	ds_read_b128 v[64:67], v14 offset:7168
	global_load_lds_dwordx4 v[68:69], off
	v_lshl_add_u64 v[68:69], s[54:55], 0, v[134:135]
	s_mov_b32 m0, s37
	s_nop 0
	global_load_lds_dwordx4 v[68:69], off
	s_waitcnt lgkmcnt(8)
	s_barrier
	s_waitcnt lgkmcnt(0)
	s_setprio 1
	s_waitcnt lgkmcnt(0)
	v_mfma_f32_16x16x32_bf16 v[68:71], v[36:39], v[18:21], 0
	v_mfma_f32_16x16x32_bf16 v[76:79], v[44:47], v[18:21], 0
	v_mfma_f32_16x16x32_bf16 v[84:87], v[52:55], v[18:21], 0
	v_mfma_f32_16x16x32_bf16 v[18:21], v[60:63], v[18:21], 0
	v_mfma_f32_16x16x32_bf16 v[68:71], v[40:43], v[22:25], v[68:71]
	v_mfma_f32_16x16x32_bf16 v[72:75], v[36:39], v[26:29], 0
	v_mfma_f32_16x16x32_bf16 v[76:79], v[48:51], v[22:25], v[76:79]
	v_mfma_f32_16x16x32_bf16 v[80:83], v[44:47], v[26:29], 0
	v_mfma_f32_16x16x32_bf16 v[84:87], v[56:59], v[22:25], v[84:87]
	v_mfma_f32_16x16x32_bf16 v[88:91], v[52:55], v[26:29], 0
	v_mfma_f32_16x16x32_bf16 v[18:21], v[64:67], v[22:25], v[18:21]
	v_mfma_f32_16x16x32_bf16 v[22:25], v[60:63], v[26:29], 0
	v_mfma_f32_16x16x32_bf16 v[72:75], v[40:43], v[30:33], v[72:75]
	v_mfma_f32_16x16x32_bf16 v[80:83], v[48:51], v[30:33], v[80:83]
	v_mfma_f32_16x16x32_bf16 v[88:91], v[56:59], v[30:33], v[88:91]
	v_mfma_f32_16x16x32_bf16 v[22:25], v[64:67], v[30:33], v[22:25]
	s_setprio 0
	s_barrier
	v_lshl_add_u64 v[136:137], s[18:19], 0, v[132:133]
	s_mov_b32 m0, s40
	v_lshl_add_u64 v[100:101], v[136:137], 0, s[6:7]
	v_lshl_add_u64 v[138:139], s[18:19], 0, v[134:135]
	ds_read_b128 v[26:29], v15
	ds_read_b128 v[30:33], v15 offset:1024
	ds_read_b128 v[92:95], v15 offset:2048
	ds_read_b128 v[96:99], v15 offset:3072
	global_load_lds_dwordx4 v[100:101], off
	v_lshl_add_u64 v[100:101], v[138:139], 0, s[6:7]
	s_mov_b32 m0, s41
	s_nop 0
	global_load_lds_dwordx4 v[100:101], off
	s_barrier
	s_waitcnt lgkmcnt(0)
	s_setprio 1
	s_waitcnt lgkmcnt(0)
	v_mfma_f32_16x16x32_bf16 v[100:103], v[36:39], v[26:29], 0
	v_mfma_f32_16x16x32_bf16 v[36:39], v[36:39], v[92:95], 0
	v_mfma_f32_16x16x32_bf16 v[100:103], v[40:43], v[30:33], v[100:103]
	v_mfma_f32_16x16x32_bf16 v[36:39], v[40:43], v[96:99], v[36:39]
	v_mfma_f32_16x16x32_bf16 v[40:43], v[44:47], v[26:29], 0
	v_mfma_f32_16x16x32_bf16 v[44:47], v[44:47], v[92:95], 0
	v_mfma_f32_16x16x32_bf16 v[40:43], v[48:51], v[30:33], v[40:43]
	v_mfma_f32_16x16x32_bf16 v[44:47], v[48:51], v[96:99], v[44:47]
	v_mfma_f32_16x16x32_bf16 v[48:51], v[52:55], v[26:29], 0
	v_mfma_f32_16x16x32_bf16 v[26:29], v[60:63], v[26:29], 0
	v_mfma_f32_16x16x32_bf16 v[48:51], v[56:59], v[30:33], v[48:51]
	v_mfma_f32_16x16x32_bf16 v[52:55], v[52:55], v[92:95], 0
	v_mfma_f32_16x16x32_bf16 v[26:29], v[64:67], v[30:33], v[26:29]
	v_mfma_f32_16x16x32_bf16 v[30:33], v[60:63], v[92:95], 0
	v_mfma_f32_16x16x32_bf16 v[52:55], v[56:59], v[96:99], v[52:55]
	v_mfma_f32_16x16x32_bf16 v[30:33], v[64:67], v[96:99], v[30:33]
	s_setprio 0
	v_lshl_add_u64 v[140:141], s[16:17], 0, v[132:133]
	s_mov_b32 m0, s5
	v_lshl_add_u64 v[56:57], v[140:141], 0, s[6:7]
	v_lshl_add_u64 v[142:143], s[16:17], 0, v[134:135]
	s_barrier
	global_load_lds_dwordx4 v[56:57], off
	v_lshl_add_u64 v[56:57], v[142:143], 0, s[6:7]
	s_mov_b32 m0, s24
	s_nop 0
	global_load_lds_dwordx4 v[56:57], off
	s_barrier
	s_waitcnt lgkmcnt(0)
	s_setprio 1
	s_setprio 0
	s_barrier
	s_add_u32 s54, s18, 0x80100
	s_addc_u32 s55, s19, 0
	s_mov_b32 m0, s42
	v_lshl_add_u64 v[56:57], s[54:55], 0, v[132:133]
	global_load_lds_dwordx4 v[56:57], off
	v_lshl_add_u64 v[56:57], s[54:55], 0, v[134:135]
	s_mov_b32 m0, s43
	s_nop 0
	global_load_lds_dwordx4 v[56:57], off
	s_waitcnt vmcnt(6)
	s_barrier
	s_setprio 1
	s_setprio 0
	s_barrier
	ds_read_b128 v[56:59], v16
	ds_read_b128 v[60:63], v16 offset:1024
	ds_read_b128 v[64:67], v16 offset:2048
	ds_read_b128 v[92:95], v16 offset:3072
	s_add_u32 s54, s16, 0x80100
	s_addc_u32 s55, s17, 0
	s_mov_b32 m0, s25
	v_lshl_add_u64 v[144:145], s[54:55], 0, v[132:133]
	ds_read_b128 v[96:99], v14 offset:32768
	ds_read_b128 v[104:107], v14 offset:33792
	ds_read_b128 v[108:111], v14 offset:34816
	ds_read_b128 v[112:115], v14 offset:35840
	ds_read_b128 v[116:119], v14 offset:36864
	ds_read_b128 v[120:123], v14 offset:37888
	ds_read_b128 v[124:127], v14 offset:38912
	ds_read_b128 v[128:131], v14 offset:39936
	global_load_lds_dwordx4 v[144:145], off
	v_lshl_add_u64 v[144:145], s[54:55], 0, v[134:135]
	s_mov_b32 m0, s26
	s_nop 0
	global_load_lds_dwordx4 v[144:145], off
	s_waitcnt lgkmcnt(8)
	s_barrier
	s_waitcnt lgkmcnt(0)
	s_setprio 1
	s_waitcnt lgkmcnt(0)
	v_mfma_f32_16x16x32_bf16 v[68:71], v[96:99], v[56:59], v[68:71]
	v_mfma_f32_16x16x32_bf16 v[72:75], v[96:99], v[64:67], v[72:75]
	v_mfma_f32_16x16x32_bf16 v[76:79], v[108:111], v[56:59], v[76:79]
	v_mfma_f32_16x16x32_bf16 v[80:83], v[108:111], v[64:67], v[80:83]
	v_mfma_f32_16x16x32_bf16 v[84:87], v[116:119], v[56:59], v[84:87]
	v_mfma_f32_16x16x32_bf16 v[88:91], v[116:119], v[64:67], v[88:91]
	v_mfma_f32_16x16x32_bf16 v[18:21], v[124:127], v[56:59], v[18:21]
	v_mfma_f32_16x16x32_bf16 v[22:25], v[124:127], v[64:67], v[22:25]
	v_mfma_f32_16x16x32_bf16 v[68:71], v[104:107], v[60:63], v[68:71]
	v_mfma_f32_16x16x32_bf16 v[72:75], v[104:107], v[92:95], v[72:75]
	v_mfma_f32_16x16x32_bf16 v[76:79], v[112:115], v[60:63], v[76:79]
	v_mfma_f32_16x16x32_bf16 v[80:83], v[112:115], v[92:95], v[80:83]
	v_mfma_f32_16x16x32_bf16 v[84:87], v[120:123], v[60:63], v[84:87]
	v_mfma_f32_16x16x32_bf16 v[88:91], v[120:123], v[92:95], v[88:91]
	v_mfma_f32_16x16x32_bf16 v[18:21], v[128:131], v[60:63], v[18:21]
	v_mfma_f32_16x16x32_bf16 v[22:25], v[128:131], v[92:95], v[22:25]
	s_setprio 0
	s_barrier
	s_mov_b32 m0, s44
	v_lshl_add_u64 v[136:137], v[136:137], 0, s[8:9]
	ds_read_b128 v[56:59], v17
	ds_read_b128 v[60:63], v17 offset:1024
	ds_read_b128 v[64:67], v17 offset:2048
	ds_read_b128 v[92:95], v17 offset:3072
	global_load_lds_dwordx4 v[136:137], off
	v_lshl_add_u64 v[136:137], v[138:139], 0, s[8:9]
	s_mov_b32 m0, s45
	s_nop 0
	global_load_lds_dwordx4 v[136:137], off
	s_barrier
	s_waitcnt lgkmcnt(0)
	s_setprio 1
	s_waitcnt lgkmcnt(0)
	v_mfma_f32_16x16x32_bf16 v[100:103], v[96:99], v[56:59], v[100:103]
	v_mfma_f32_16x16x32_bf16 v[36:39], v[96:99], v[64:67], v[36:39]
	v_mfma_f32_16x16x32_bf16 v[40:43], v[108:111], v[56:59], v[40:43]
	v_mfma_f32_16x16x32_bf16 v[44:47], v[108:111], v[64:67], v[44:47]
	v_mfma_f32_16x16x32_bf16 v[48:51], v[116:119], v[56:59], v[48:51]
	v_mfma_f32_16x16x32_bf16 v[52:55], v[116:119], v[64:67], v[52:55]
	v_mfma_f32_16x16x32_bf16 v[26:29], v[124:127], v[56:59], v[26:29]
	v_mfma_f32_16x16x32_bf16 v[30:33], v[124:127], v[64:67], v[30:33]
	v_mfma_f32_16x16x32_bf16 v[100:103], v[104:107], v[60:63], v[100:103]
	v_mfma_f32_16x16x32_bf16 v[36:39], v[104:107], v[92:95], v[36:39]
	v_mfma_f32_16x16x32_bf16 v[40:43], v[112:115], v[60:63], v[40:43]
	v_mfma_f32_16x16x32_bf16 v[44:47], v[112:115], v[92:95], v[44:47]
	v_mfma_f32_16x16x32_bf16 v[48:51], v[120:123], v[60:63], v[48:51]
	v_mfma_f32_16x16x32_bf16 v[52:55], v[120:123], v[92:95], v[52:55]
	v_mfma_f32_16x16x32_bf16 v[26:29], v[128:131], v[60:63], v[26:29]
	v_mfma_f32_16x16x32_bf16 v[30:33], v[128:131], v[92:95], v[30:33]
	s_setprio 0
	s_mov_b32 m0, s27
	v_lshl_add_u64 v[56:57], v[140:141], 0, s[8:9]
	s_barrier
	global_load_lds_dwordx4 v[56:57], off
	v_lshl_add_u64 v[56:57], v[142:143], 0, s[8:9]
	s_mov_b32 m0, s29
	s_nop 0
	global_load_lds_dwordx4 v[56:57], off
	s_barrier
	s_waitcnt lgkmcnt(0)
	s_setprio 1
	s_setprio 0
	s_barrier
	s_add_u32 s18, s18, 0x80180
	s_addc_u32 s19, s19, 0
	s_mov_b32 m0, s46
	v_lshl_add_u64 v[56:57], s[18:19], 0, v[132:133]
	global_load_lds_dwordx4 v[56:57], off
	v_lshl_add_u64 v[56:57], s[18:19], 0, v[134:135]
	s_mov_b32 m0, s47
	s_nop 0
	global_load_lds_dwordx4 v[56:57], off
	s_waitcnt vmcnt(6)
	s_barrier
	s_setprio 1
	s_setprio 0
	s_barrier
	ds_read_b128 v[56:59], v13
	ds_read_b128 v[60:63], v13 offset:1024
	ds_read_b128 v[64:67], v13 offset:2048
	ds_read_b128 v[92:95], v13 offset:3072
	s_add_u32 s16, s16, 0x80180
	s_addc_u32 s17, s17, 0
	s_mov_b32 m0, s36
	v_lshl_add_u64 v[136:137], s[16:17], 0, v[132:133]
	ds_read_b128 v[96:99], v14
	ds_read_b128 v[104:107], v14 offset:1024
	ds_read_b128 v[108:111], v14 offset:2048
	ds_read_b128 v[112:115], v14 offset:3072
	ds_read_b128 v[116:119], v14 offset:4096
	ds_read_b128 v[120:123], v14 offset:5120
	ds_read_b128 v[124:127], v14 offset:6144
	ds_read_b128 v[128:131], v14 offset:7168
	global_load_lds_dwordx4 v[136:137], off
	v_lshl_add_u64 v[136:137], s[16:17], 0, v[134:135]
	s_mov_b32 m0, s37
	s_nop 0
	global_load_lds_dwordx4 v[136:137], off
	s_waitcnt lgkmcnt(8)
	s_barrier
	s_waitcnt lgkmcnt(0)
	s_setprio 1
	s_waitcnt lgkmcnt(0)
	v_mfma_f32_16x16x32_bf16 v[68:71], v[96:99], v[56:59], v[68:71]
	v_mfma_f32_16x16x32_bf16 v[72:75], v[96:99], v[64:67], v[72:75]
	v_mfma_f32_16x16x32_bf16 v[76:79], v[108:111], v[56:59], v[76:79]
	v_mfma_f32_16x16x32_bf16 v[80:83], v[108:111], v[64:67], v[80:83]
	v_mfma_f32_16x16x32_bf16 v[84:87], v[116:119], v[56:59], v[84:87]
	v_mfma_f32_16x16x32_bf16 v[88:91], v[116:119], v[64:67], v[88:91]
	v_mfma_f32_16x16x32_bf16 v[18:21], v[124:127], v[56:59], v[18:21]
	v_mfma_f32_16x16x32_bf16 v[22:25], v[124:127], v[64:67], v[22:25]
	v_mfma_f32_16x16x32_bf16 v[68:71], v[104:107], v[60:63], v[68:71]
	v_mfma_f32_16x16x32_bf16 v[72:75], v[104:107], v[92:95], v[72:75]
	v_mfma_f32_16x16x32_bf16 v[76:79], v[112:115], v[60:63], v[76:79]
	v_mfma_f32_16x16x32_bf16 v[80:83], v[112:115], v[92:95], v[80:83]
	v_mfma_f32_16x16x32_bf16 v[84:87], v[120:123], v[60:63], v[84:87]
	v_mfma_f32_16x16x32_bf16 v[88:91], v[120:123], v[92:95], v[88:91]
	v_mfma_f32_16x16x32_bf16 v[18:21], v[128:131], v[60:63], v[18:21]
	v_mfma_f32_16x16x32_bf16 v[22:25], v[128:131], v[92:95], v[22:25]
	s_setprio 0
	s_barrier
	s_mov_b32 m0, s40
	v_lshl_add_u64 v[136:137], s[14:15], 0, v[132:133]
	ds_read_b128 v[56:59], v15
	ds_read_b128 v[60:63], v15 offset:1024
	ds_read_b128 v[64:67], v15 offset:2048
	ds_read_b128 v[92:95], v15 offset:3072
	global_load_lds_dwordx4 v[136:137], off
	v_lshl_add_u64 v[138:139], s[14:15], 0, v[134:135]
	s_mov_b32 m0, s41
	s_nop 0
	global_load_lds_dwordx4 v[138:139], off
	s_barrier
	s_waitcnt lgkmcnt(0)
	s_setprio 1
	s_waitcnt lgkmcnt(0)
	v_mfma_f32_16x16x32_bf16 v[100:103], v[96:99], v[56:59], v[100:103]
	v_mfma_f32_16x16x32_bf16 v[36:39], v[96:99], v[64:67], v[36:39]
	v_mfma_f32_16x16x32_bf16 v[40:43], v[108:111], v[56:59], v[40:43]
	v_mfma_f32_16x16x32_bf16 v[44:47], v[108:111], v[64:67], v[44:47]
	v_mfma_f32_16x16x32_bf16 v[48:51], v[116:119], v[56:59], v[48:51]
	v_mfma_f32_16x16x32_bf16 v[52:55], v[116:119], v[64:67], v[52:55]
	v_mfma_f32_16x16x32_bf16 v[26:29], v[124:127], v[56:59], v[26:29]
	v_mfma_f32_16x16x32_bf16 v[30:33], v[124:127], v[64:67], v[30:33]
	v_mfma_f32_16x16x32_bf16 v[100:103], v[104:107], v[60:63], v[100:103]
	v_mfma_f32_16x16x32_bf16 v[36:39], v[104:107], v[92:95], v[36:39]
	v_mfma_f32_16x16x32_bf16 v[40:43], v[112:115], v[60:63], v[40:43]
	v_mfma_f32_16x16x32_bf16 v[44:47], v[112:115], v[92:95], v[44:47]
	v_mfma_f32_16x16x32_bf16 v[48:51], v[120:123], v[60:63], v[48:51]
	v_mfma_f32_16x16x32_bf16 v[52:55], v[120:123], v[92:95], v[52:55]
	v_mfma_f32_16x16x32_bf16 v[26:29], v[128:131], v[60:63], v[26:29]
	v_mfma_f32_16x16x32_bf16 v[30:33], v[128:131], v[92:95], v[30:33]
	s_setprio 0
	s_mov_b32 m0, s5
	v_lshl_add_u64 v[140:141], s[20:21], 0, v[132:133]
	s_barrier
	global_load_lds_dwordx4 v[140:141], off
	v_lshl_add_u64 v[142:143], s[20:21], 0, v[134:135]
	s_mov_b32 m0, s24
	s_nop 0
	global_load_lds_dwordx4 v[142:143], off
	s_barrier
	s_waitcnt lgkmcnt(0)
	s_setprio 1
	s_setprio 0
	s_barrier
	s_add_u32 s16, s14, 0x80000
	s_addc_u32 s17, s15, 0
	s_mov_b32 m0, s42
	v_lshl_add_u64 v[56:57], s[16:17], 0, v[132:133]
	global_load_lds_dwordx4 v[56:57], off
	v_lshl_add_u64 v[56:57], s[16:17], 0, v[134:135]
	s_mov_b32 m0, s43
	s_nop 0
	global_load_lds_dwordx4 v[56:57], off
	s_waitcnt vmcnt(6)
	s_barrier
	s_setprio 1
	s_setprio 0
	s_barrier
	ds_read_b128 v[56:59], v16
	ds_read_b128 v[60:63], v16 offset:1024
	ds_read_b128 v[64:67], v16 offset:2048
	ds_read_b128 v[92:95], v16 offset:3072
	s_add_u32 s16, s20, 0x80000
	s_addc_u32 s17, s21, 0
	s_mov_b32 m0, s25
	v_lshl_add_u64 v[144:145], s[16:17], 0, v[132:133]
	ds_read_b128 v[96:99], v14 offset:32768
	ds_read_b128 v[104:107], v14 offset:33792
	ds_read_b128 v[108:111], v14 offset:34816
	ds_read_b128 v[112:115], v14 offset:35840
	ds_read_b128 v[116:119], v14 offset:36864
	ds_read_b128 v[120:123], v14 offset:37888
	ds_read_b128 v[124:127], v14 offset:38912
	ds_read_b128 v[128:131], v14 offset:39936
	global_load_lds_dwordx4 v[144:145], off
	v_lshl_add_u64 v[144:145], s[16:17], 0, v[134:135]
	s_mov_b32 m0, s26
	s_nop 0
	global_load_lds_dwordx4 v[144:145], off
	s_waitcnt lgkmcnt(8)
	s_barrier
	s_waitcnt lgkmcnt(0)
	s_setprio 1
	s_waitcnt lgkmcnt(0)
	v_mfma_f32_16x16x32_bf16 v[68:71], v[96:99], v[56:59], v[68:71]
	v_mfma_f32_16x16x32_bf16 v[72:75], v[96:99], v[64:67], v[72:75]
	v_mfma_f32_16x16x32_bf16 v[76:79], v[108:111], v[56:59], v[76:79]
	v_mfma_f32_16x16x32_bf16 v[80:83], v[108:111], v[64:67], v[80:83]
	v_mfma_f32_16x16x32_bf16 v[84:87], v[116:119], v[56:59], v[84:87]
	v_mfma_f32_16x16x32_bf16 v[88:91], v[116:119], v[64:67], v[88:91]
	v_mfma_f32_16x16x32_bf16 v[18:21], v[124:127], v[56:59], v[18:21]
	v_mfma_f32_16x16x32_bf16 v[22:25], v[124:127], v[64:67], v[22:25]
	v_mfma_f32_16x16x32_bf16 v[68:71], v[104:107], v[60:63], v[68:71]
	v_mfma_f32_16x16x32_bf16 v[72:75], v[104:107], v[92:95], v[72:75]
	v_mfma_f32_16x16x32_bf16 v[76:79], v[112:115], v[60:63], v[76:79]
	v_mfma_f32_16x16x32_bf16 v[80:83], v[112:115], v[92:95], v[80:83]
	v_mfma_f32_16x16x32_bf16 v[84:87], v[120:123], v[60:63], v[84:87]
	v_mfma_f32_16x16x32_bf16 v[88:91], v[120:123], v[92:95], v[88:91]
	v_mfma_f32_16x16x32_bf16 v[18:21], v[128:131], v[60:63], v[18:21]
	v_mfma_f32_16x16x32_bf16 v[22:25], v[128:131], v[92:95], v[22:25]
	s_setprio 0
	s_barrier
	s_mov_b32 m0, s44
	v_lshl_add_u64 v[136:137], v[136:137], 0, s[0:1]
	ds_read_b128 v[56:59], v17
	ds_read_b128 v[60:63], v17 offset:1024
	ds_read_b128 v[64:67], v17 offset:2048
	ds_read_b128 v[92:95], v17 offset:3072
	global_load_lds_dwordx4 v[136:137], off
	v_lshl_add_u64 v[136:137], v[138:139], 0, s[0:1]
	s_mov_b32 m0, s45
	s_nop 0
	global_load_lds_dwordx4 v[136:137], off
	s_barrier
	s_waitcnt lgkmcnt(0)
	s_setprio 1
	s_waitcnt lgkmcnt(0)
	v_mfma_f32_16x16x32_bf16 v[100:103], v[96:99], v[56:59], v[100:103]
	v_mfma_f32_16x16x32_bf16 v[36:39], v[96:99], v[64:67], v[36:39]
	v_mfma_f32_16x16x32_bf16 v[40:43], v[108:111], v[56:59], v[40:43]
	v_mfma_f32_16x16x32_bf16 v[44:47], v[108:111], v[64:67], v[44:47]
	v_mfma_f32_16x16x32_bf16 v[48:51], v[116:119], v[56:59], v[48:51]
	v_mfma_f32_16x16x32_bf16 v[52:55], v[116:119], v[64:67], v[52:55]
	v_mfma_f32_16x16x32_bf16 v[26:29], v[124:127], v[56:59], v[26:29]
	v_mfma_f32_16x16x32_bf16 v[30:33], v[124:127], v[64:67], v[30:33]
	v_mfma_f32_16x16x32_bf16 v[100:103], v[104:107], v[60:63], v[100:103]
	v_mfma_f32_16x16x32_bf16 v[36:39], v[104:107], v[92:95], v[36:39]
	v_mfma_f32_16x16x32_bf16 v[40:43], v[112:115], v[60:63], v[40:43]
	v_mfma_f32_16x16x32_bf16 v[44:47], v[112:115], v[92:95], v[44:47]
	v_mfma_f32_16x16x32_bf16 v[48:51], v[120:123], v[60:63], v[48:51]
	v_mfma_f32_16x16x32_bf16 v[52:55], v[120:123], v[92:95], v[52:55]
	v_mfma_f32_16x16x32_bf16 v[26:29], v[128:131], v[60:63], v[26:29]
	v_mfma_f32_16x16x32_bf16 v[30:33], v[128:131], v[92:95], v[30:33]
	s_setprio 0
	s_mov_b32 m0, s27
	v_lshl_add_u64 v[56:57], v[140:141], 0, s[0:1]
	s_barrier
	global_load_lds_dwordx4 v[56:57], off
	v_lshl_add_u64 v[56:57], v[142:143], 0, s[0:1]
	s_mov_b32 m0, s29
	s_nop 0
	global_load_lds_dwordx4 v[56:57], off
	s_barrier
	s_waitcnt lgkmcnt(0)
	s_setprio 1
	s_setprio 0
	s_barrier
	s_add_u32 s14, s14, 0x80080
	s_addc_u32 s15, s15, 0
	s_mov_b32 m0, s46
	v_lshl_add_u64 v[56:57], s[14:15], 0, v[132:133]
	global_load_lds_dwordx4 v[56:57], off
	v_lshl_add_u64 v[56:57], s[14:15], 0, v[134:135]
	s_mov_b32 m0, s47
	s_nop 0
	global_load_lds_dwordx4 v[56:57], off
	s_waitcnt vmcnt(6)
	s_barrier
	s_setprio 1
	s_setprio 0
	v_lshl_or_b32 v2, s30, 8, v12
	v_lshlrev_b64 v[56:57], 2, v[2:3]
	v_lshl_add_u64 v[58:59], v[4:5], 0, v[56:57]
	s_barrier
	v_mov_b32_e32 v62, 0x2000
	v_mov_b32_e32 v63, 0
	v_mov_b32_e32 v56, 0x1a000
	v_mov_b32_e32 v57, 0
	v_mbcnt_lo_u32_b32 v60, -1, 0
	v_mbcnt_hi_u32_b32 v60, -1, v60
	v_and_b32_e32 v61, 15, v60
	v_lshrrev_b32_e32 v60, 4, v60
	v_lshlrev_b32_e32 v60, 2, v60
	v_sub_u32_e32 v60, v60, v61
	v_mul_i32_i24_e32 v60, 0x1ffc, v60
	v_ashrrev_i32_e32 v61, 31, v60
	v_lshl_add_u64 v[58:59], v[60:61], 0, v[58:59]
	global_atomic_add_f32 v[58:59], v68, off
	global_atomic_add_f32 v[58:59], v72, off offset:64
	global_atomic_add_f32 v[58:59], v100, off offset:512
	global_atomic_add_f32 v[58:59], v36, off offset:576
	v_lshl_add_u64 v[60:61], v[58:59], 0, v[62:63]
	global_atomic_add_f32 v[60:61], v69, off
	global_atomic_add_f32 v[60:61], v73, off offset:64
	global_atomic_add_f32 v[60:61], v101, off offset:512
	global_atomic_add_f32 v[60:61], v37, off offset:576
	v_lshl_add_u64 v[58:59], v[60:61], 0, v[62:63]
	global_atomic_add_f32 v[58:59], v70, off
	global_atomic_add_f32 v[58:59], v74, off offset:64
	global_atomic_add_f32 v[58:59], v102, off offset:512
	global_atomic_add_f32 v[58:59], v38, off offset:576
	v_lshl_add_u64 v[60:61], v[58:59], 0, v[62:63]
	global_atomic_add_f32 v[60:61], v71, off
	global_atomic_add_f32 v[60:61], v75, off offset:64
	global_atomic_add_f32 v[60:61], v103, off offset:512
	global_atomic_add_f32 v[60:61], v39, off offset:576
	v_lshl_add_u64 v[58:59], v[60:61], 0, v[56:57]
	global_atomic_add_f32 v[58:59], v76, off
	global_atomic_add_f32 v[58:59], v80, off offset:64
	global_atomic_add_f32 v[58:59], v40, off offset:512
	global_atomic_add_f32 v[58:59], v44, off offset:576
	v_lshl_add_u64 v[60:61], v[58:59], 0, v[62:63]
	global_atomic_add_f32 v[60:61], v77, off
	global_atomic_add_f32 v[60:61], v81, off offset:64
	global_atomic_add_f32 v[60:61], v41, off offset:512
	global_atomic_add_f32 v[60:61], v45, off offset:576
	v_lshl_add_u64 v[58:59], v[60:61], 0, v[62:63]
	global_atomic_add_f32 v[58:59], v78, off
	global_atomic_add_f32 v[58:59], v82, off offset:64
	global_atomic_add_f32 v[58:59], v42, off offset:512
	global_atomic_add_f32 v[58:59], v46, off offset:576
	v_lshl_add_u64 v[60:61], v[58:59], 0, v[62:63]
	global_atomic_add_f32 v[60:61], v79, off
	global_atomic_add_f32 v[60:61], v83, off offset:64
	global_atomic_add_f32 v[60:61], v43, off offset:512
	global_atomic_add_f32 v[60:61], v47, off offset:576
	v_lshl_add_u64 v[58:59], v[60:61], 0, v[56:57]
	global_atomic_add_f32 v[58:59], v84, off
	global_atomic_add_f32 v[58:59], v88, off offset:64
	global_atomic_add_f32 v[58:59], v48, off offset:512
	global_atomic_add_f32 v[58:59], v52, off offset:576
	v_lshl_add_u64 v[60:61], v[58:59], 0, v[62:63]
	global_atomic_add_f32 v[60:61], v85, off
	global_atomic_add_f32 v[60:61], v89, off offset:64
	global_atomic_add_f32 v[60:61], v49, off offset:512
	global_atomic_add_f32 v[60:61], v53, off offset:576
	v_lshl_add_u64 v[58:59], v[60:61], 0, v[62:63]
	global_atomic_add_f32 v[58:59], v86, off
	global_atomic_add_f32 v[58:59], v90, off offset:64
	global_atomic_add_f32 v[58:59], v50, off offset:512
	global_atomic_add_f32 v[58:59], v54, off offset:576
	v_lshl_add_u64 v[60:61], v[58:59], 0, v[62:63]
	global_atomic_add_f32 v[60:61], v87, off
	global_atomic_add_f32 v[60:61], v91, off offset:64
	global_atomic_add_f32 v[60:61], v51, off offset:512
	global_atomic_add_f32 v[60:61], v55, off offset:576
	v_lshl_add_u64 v[58:59], v[60:61], 0, v[56:57]
	global_atomic_add_f32 v[58:59], v18, off
	global_atomic_add_f32 v[58:59], v22, off offset:64
	global_atomic_add_f32 v[58:59], v26, off offset:512
	global_atomic_add_f32 v[58:59], v30, off offset:576
	v_lshl_add_u64 v[60:61], v[58:59], 0, v[62:63]
	global_atomic_add_f32 v[60:61], v19, off
	global_atomic_add_f32 v[60:61], v23, off offset:64
	global_atomic_add_f32 v[60:61], v27, off offset:512
	global_atomic_add_f32 v[60:61], v31, off offset:576
	v_lshl_add_u64 v[58:59], v[60:61], 0, v[62:63]
	global_atomic_add_f32 v[58:59], v20, off
	global_atomic_add_f32 v[58:59], v24, off offset:64
	global_atomic_add_f32 v[58:59], v28, off offset:512
	global_atomic_add_f32 v[58:59], v32, off offset:576
	v_lshl_add_u64 v[60:61], v[58:59], 0, v[62:63]
	global_atomic_add_f32 v[60:61], v21, off
	global_atomic_add_f32 v[60:61], v25, off offset:64
	global_atomic_add_f32 v[60:61], v29, off offset:512
	global_atomic_add_f32 v[60:61], v33, off offset:576
	s_add_i32 s31, s31, s33
	s_mov_b32 s30, s49
	s_mov_b32 s14, s52
	s_mov_b64 s[18:19], s[10:11]
	s_mov_b64 s[16:17], s[12:13]
	s_cbranch_vccnz .LBB0_2174
	s_waitcnt vmcnt(0)
	s_cmpk_gt_u32 s2, 0xff
	s_cbranch_scc1 .LBB0_2177
	s_barrier

.LBB0_2502:
	v_lshl_add_u64 v[48:49], v[40:41], 0, v[92:93]
	v_add_co_u32_e32 v134, vcc, s30, v48
	v_pk_fma_f32 v[76:77], v[42:43], v[124:125], v[38:39]
	s_nop 0
	v_addc_co_u32_e32 v135, vcc, 0, v49, vcc
	v_pk_fma_f32 v[78:79], v[6:7], v[122:123], v[30:31]
	v_pk_fma_f32 v[80:81], v[56:57], v[120:121], v[52:53]
	v_pk_fma_f32 v[82:83], v[8:9], v[118:119], v[32:33]
	v_add_co_u32_e32 v136, vcc, s33, v48
	v_pk_fma_f32 v[118:119], v[42:43], v[94:95], v[38:39]
	v_pk_fma_f32 v[120:121], v[6:7], v[96:97], v[30:31]
	v_pk_fma_f32 v[122:123], v[56:57], v[98:99], v[52:53]
	v_pk_fma_f32 v[124:125], v[8:9], v[100:101], v[32:33]
	v_addc_co_u32_e32 v137, vcc, 0, v49, vcc
	v_pk_fma_f32 v[138:139], v[46:47], v[94:95], v[76:77]
	v_pk_fma_f32 v[140:141], v[14:15], v[96:97], v[78:79]
	v_pk_fma_f32 v[98:99], v[60:61], v[98:99], v[80:81]
	v_pk_fma_f32 v[100:101], v[16:17], v[100:101], v[82:83]
	global_load_dwordx4 v[80:83], v[134:135], off offset:512 nt
	global_load_dwordx4 v[94:97], v[136:137], off offset:3584 nt
	v_pk_fma_f32 v[110:111], v[58:59], v[110:111], v[54:55]
	v_pk_fma_f32 v[112:113], v[2:3], v[112:113], v[26:27]
	v_pk_fma_f32 v[114:115], v[66:67], v[114:115], v[64:65]
	v_pk_fma_f32 v[116:117], v[4:5], v[116:117], v[28:29]
	v_pk_fma_f32 v[126:127], v[58:59], v[102:103], v[54:55]
	v_pk_fma_f32 v[102:103], v[62:63], v[102:103], v[110:111]
	v_pk_fma_f32 v[128:129], v[2:3], v[104:105], v[26:27]
	v_pk_fma_f32 v[130:131], v[66:67], v[106:107], v[64:65]
	v_pk_fma_f32 v[132:133], v[4:5], v[108:109], v[28:29]
	v_pk_fma_f32 v[104:105], v[10:11], v[104:105], v[112:113]
	v_pk_fma_f32 v[106:107], v[72:73], v[106:107], v[114:115]
	v_pk_fma_f32 v[108:109], v[12:13], v[108:109], v[116:117]
	v_lshl_add_u64 v[44:45], v[36:37], 0, v[92:93]
	v_add_co_u32_e32 v110, vcc, s36, v44
	s_add_i32 s0, s0, -4
	s_nop 0
	v_addc_co_u32_e32 v111, vcc, 0, v45, vcc
	v_add_co_u32_e32 v112, vcc, s37, v48
	v_lshl_add_u64 v[36:37], v[36:37], 0, s[12:13]
	s_nop 0
	v_addc_co_u32_e32 v113, vcc, 0, v49, vcc
	v_add_co_u32_e32 v114, vcc, s38, v48
	v_lshl_add_u64 v[40:41], v[40:41], 0, s[16:17]
	s_nop 0
	v_addc_co_u32_e32 v115, vcc, 0, v49, vcc
	v_add_co_u32_e32 v116, vcc, s39, v44
	s_cmp_eq_u32 s0, 0
	s_nop 0
	v_addc_co_u32_e32 v117, vcc, 0, v45, vcc
	v_add_co_u32_e32 v142, vcc, s40, v48
	s_waitcnt vmcnt(0)
	v_lshlrev_b32_e32 v135, 16, v80
	v_lshlrev_b32_e32 v134, 16, v94
	v_and_b32_e32 v137, 0xffff0000, v80
	v_and_b32_e32 v136, 0xffff0000, v94
	v_lshlrev_b32_e32 v147, 16, v81
	v_lshlrev_b32_e32 v146, 16, v95
	v_and_b32_e32 v81, 0xffff0000, v81
	v_and_b32_e32 v80, 0xffff0000, v95
	v_lshlrev_b32_e32 v95, 16, v82
	v_lshlrev_b32_e32 v94, 16, v96
	v_and_b32_e32 v149, 0xffff0000, v82
	v_and_b32_e32 v148, 0xffff0000, v96
	v_lshlrev_b32_e32 v151, 16, v83
	v_lshlrev_b32_e32 v150, 16, v97
	v_and_b32_e32 v83, 0xffff0000, v83
	v_and_b32_e32 v82, 0xffff0000, v97
	v_pk_fma_f32 v[96:97], v[50:51], v[134:135], v[138:139]
	v_pk_fma_f32 v[138:139], v[22:23], v[136:137], v[140:141]
	v_pk_fma_f32 v[98:99], v[68:69], v[146:147], v[98:99]
	v_pk_fma_f32 v[100:101], v[24:25], v[80:81], v[100:101]
	v_pk_fma_f32 v[102:103], v[70:71], v[94:95], v[102:103]
	v_pk_fma_f32 v[104:105], v[18:19], v[148:149], v[104:105]
	v_pk_fma_f32 v[106:107], v[74:75], v[150:151], v[106:107]
	v_pk_fma_f32 v[108:109], v[20:21], v[82:83], v[108:109]
	v_pk_fma_f32 v[122:123], v[60:61], v[146:147], v[122:123]
	v_pk_fma_f32 v[124:125], v[16:17], v[80:81], v[124:125]
	v_pk_fma_f32 v[132:133], v[12:13], v[82:83], v[132:133]
	v_pk_fma_f32 v[140:141], v[56:57], v[146:147], v[52:53]
	v_pk_fma_f32 v[146:147], v[8:9], v[80:81], v[32:33]
	v_pk_fma_f32 v[154:155], v[4:5], v[82:83], v[28:29]
	v_mul_f32_e32 v80, 0xbfb8aa3b, v139
	v_mul_f32_e32 v81, 0xbfb8aa3b, v99
	v_mul_f32_e32 v82, 0xbfb8aa3b, v101
	v_mul_f32_e32 v83, 0xbfb8aa3b, v103
	v_pk_fma_f32 v[126:127], v[62:63], v[94:95], v[126:127]
	v_pk_fma_f32 v[152:153], v[58:59], v[94:95], v[54:55]
	v_mul_f32_e32 v35, 0xbfb8aa3b, v97
	v_mul_f32_e32 v86, 0xbfb8aa3b, v105
	v_mul_f32_e32 v94, 0xbfb8aa3b, v107
	v_mul_f32_e32 v95, 0xbfb8aa3b, v109
	v_exp_f32_e32 v80, v80
	v_exp_f32_e32 v81, v81
	v_exp_f32_e32 v82, v82
	v_exp_f32_e32 v83, v83
	v_exp_f32_e32 v35, v35
	v_exp_f32_e32 v86, v86
	v_exp_f32_e32 v94, v94
	v_exp_f32_e32 v95, v95
	v_add_f32_e32 v80, 1.0, v80
	v_add_f32_e32 v81, 1.0, v81
	v_add_f32_e32 v82, 1.0, v82
	v_add_f32_e32 v83, 1.0, v83
	v_add_f32_e32 v35, 1.0, v35
	v_add_f32_e32 v86, 1.0, v86
	v_add_f32_e32 v94, 1.0, v94
	v_add_f32_e32 v95, 1.0, v95
	v_rcp_f32_e32 v80, v80
	v_rcp_f32_e32 v81, v81
	v_rcp_f32_e32 v82, v82
	v_rcp_f32_e32 v83, v83
	v_rcp_f32_e32 v35, v35
	v_rcp_f32_e32 v86, v86
	v_rcp_f32_e32 v94, v94
	v_rcp_f32_e32 v95, v95
	v_mul_f32_e32 v80, v139, v80
	v_mul_f32_e32 v81, v99, v81
	v_mul_f32_e32 v82, v101, v82
	v_mul_f32_e32 v83, v103, v83
	v_mul_f32_e32 v35, v97, v35
	v_mul_f32_e32 v86, v105, v86
	v_mul_f32_e32 v94, v107, v94
	v_mul_f32_e32 v95, v109, v95
	v_mul_f32_e32 v80, v138, v80
	v_mul_f32_e32 v81, v98, v81
	v_mul_f32_e32 v82, v100, v82
	v_mul_f32_e32 v83, v102, v83
	v_mul_f32_e32 v35, v96, v35
	v_mul_f32_e32 v86, v104, v86
	v_mul_f32_e32 v94, v106, v94
	v_mul_f32_e32 v95, v108, v95
	v_cvt_pk_bf16_f32 v80, v35, v80
	v_cvt_pk_bf16_f32 v81, v81, v82
	v_cvt_pk_bf16_f32 v82, v83, v86
	v_cvt_pk_bf16_f32 v83, v94, v95
	global_store_dwordx4 v[110:111], v[80:83], off offset:512 sc1
	global_load_dwordx4 v[80:83], v[112:113], off offset:2560 nt
	s_nop 0
	global_load_dwordx4 v[94:97], v[114:115], off offset:1536 nt
	v_pk_fma_f32 v[118:119], v[46:47], v[134:135], v[118:119]
	v_pk_fma_f32 v[120:121], v[14:15], v[136:137], v[120:121]
	v_pk_fma_f32 v[128:129], v[10:11], v[148:149], v[128:129]
	v_pk_fma_f32 v[130:131], v[72:73], v[150:151], v[130:131]
	v_addc_co_u32_e32 v143, vcc, 0, v49, vcc
	v_add_co_u32_e32 v144, vcc, s41, v48
	v_pk_fma_f32 v[134:135], v[42:43], v[134:135], v[38:39]
	s_nop 0
	v_addc_co_u32_e32 v145, vcc, 0, v49, vcc
	v_pk_fma_f32 v[136:137], v[6:7], v[136:137], v[30:31]
	v_pk_fma_f32 v[148:149], v[2:3], v[148:149], v[26:27]
	v_pk_fma_f32 v[150:151], v[66:67], v[150:151], v[64:65]
	v_add_co_u32_e32 v76, vcc, s42, v44
	s_waitcnt vmcnt(0)
	v_lshlrev_b32_e32 v99, 16, v80
	v_lshlrev_b32_e32 v98, 16, v94
	v_and_b32_e32 v101, 0xffff0000, v80
	v_and_b32_e32 v100, 0xffff0000, v94
	v_lshlrev_b32_e32 v103, 16, v81
	v_lshlrev_b32_e32 v102, 16, v95
	v_and_b32_e32 v105, 0xffff0000, v81
	v_and_b32_e32 v104, 0xffff0000, v95
	v_lshlrev_b32_e32 v107, 16, v82
	v_lshlrev_b32_e32 v106, 16, v96
	v_and_b32_e32 v109, 0xffff0000, v82
	v_and_b32_e32 v108, 0xffff0000, v96
	v_lshlrev_b32_e32 v139, 16, v83
	v_lshlrev_b32_e32 v138, 16, v97
	v_and_b32_e32 v159, 0xffff0000, v83
	v_and_b32_e32 v158, 0xffff0000, v97
	v_pk_fma_f32 v[80:81], v[50:51], v[98:99], v[118:119]
	v_pk_fma_f32 v[82:83], v[22:23], v[100:101], v[120:121]
	v_pk_fma_f32 v[94:95], v[68:69], v[102:103], v[122:123]
	v_pk_fma_f32 v[96:97], v[24:25], v[104:105], v[124:125]
	v_pk_fma_f32 v[110:111], v[70:71], v[106:107], v[126:127]
	v_pk_fma_f32 v[112:113], v[18:19], v[108:109], v[128:129]
	v_pk_fma_f32 v[114:115], v[74:75], v[138:139], v[130:131]
	v_pk_fma_f32 v[118:119], v[20:21], v[158:159], v[132:133]
	v_mul_f32_e32 v35, 0xbfb8aa3b, v81
	v_mul_f32_e32 v86, 0xbfb8aa3b, v83
	v_mul_f32_e32 v120, 0xbfb8aa3b, v95
	v_mul_f32_e32 v121, 0xbfb8aa3b, v97
	v_mul_f32_e32 v122, 0xbfb8aa3b, v111
	v_mul_f32_e32 v123, 0xbfb8aa3b, v113
	v_mul_f32_e32 v124, 0xbfb8aa3b, v115
	v_mul_f32_e32 v125, 0xbfb8aa3b, v119
	v_exp_f32_e32 v35, v35
	v_exp_f32_e32 v86, v86
	v_exp_f32_e32 v120, v120
	v_exp_f32_e32 v121, v121
	v_exp_f32_e32 v122, v122
	v_exp_f32_e32 v123, v123
	v_exp_f32_e32 v124, v124
	v_exp_f32_e32 v125, v125
	v_add_f32_e32 v35, 1.0, v35
	v_add_f32_e32 v86, 1.0, v86
	v_add_f32_e32 v120, 1.0, v120
	v_add_f32_e32 v121, 1.0, v121
	v_add_f32_e32 v122, 1.0, v122
	v_add_f32_e32 v123, 1.0, v123
	v_add_f32_e32 v124, 1.0, v124
	v_add_f32_e32 v125, 1.0, v125
	v_rcp_f32_e32 v35, v35
	v_rcp_f32_e32 v86, v86
	v_rcp_f32_e32 v120, v120
	v_rcp_f32_e32 v121, v121
	v_rcp_f32_e32 v122, v122
	v_rcp_f32_e32 v123, v123
	v_rcp_f32_e32 v124, v124
	v_rcp_f32_e32 v125, v125
	v_mul_f32_e32 v35, v81, v35
	v_mul_f32_e32 v81, v83, v86
	v_mul_f32_e32 v83, v95, v120
	v_mul_f32_e32 v86, v97, v121
	v_mul_f32_e32 v95, v111, v122
	v_mul_f32_e32 v97, v113, v123
	v_mul_f32_e32 v111, v115, v124
	v_mul_f32_e32 v113, v119, v125
	v_mul_f32_e32 v35, v80, v35
	v_mul_f32_e32 v80, v82, v81
	v_mul_f32_e32 v81, v94, v83
	v_mul_f32_e32 v82, v96, v86
	v_mul_f32_e32 v83, v110, v95
	v_mul_f32_e32 v86, v112, v97
	v_mul_f32_e32 v94, v114, v111
	v_mul_f32_e32 v95, v118, v113
	v_cvt_pk_bf16_f32 v80, v35, v80
	v_cvt_pk_bf16_f32 v81, v81, v82
	v_cvt_pk_bf16_f32 v82, v83, v86
	v_cvt_pk_bf16_f32 v83, v94, v95
	global_store_dwordx4 v[116:117], v[80:83], off offset:3584 sc1
	global_load_dwordx4 v[80:83], v[142:143], off offset:512 nt
	s_nop 0
	global_load_dwordx4 v[94:97], v[144:145], off offset:3584 nt
	v_pk_fma_f32 v[126:127], v[46:47], v[98:99], v[134:135]
	v_pk_fma_f32 v[128:129], v[14:15], v[100:101], v[136:137]
	v_pk_fma_f32 v[130:131], v[60:61], v[102:103], v[140:141]
	v_pk_fma_f32 v[132:133], v[16:17], v[104:105], v[146:147]
	v_pk_fma_f32 v[134:135], v[62:63], v[106:107], v[152:153]
	v_pk_fma_f32 v[136:137], v[10:11], v[108:109], v[148:149]
	v_pk_fma_f32 v[140:141], v[72:73], v[138:139], v[150:151]
	v_pk_fma_f32 v[146:147], v[12:13], v[158:159], v[154:155]
	v_addc_co_u32_e32 v77, vcc, 0, v45, vcc
	v_add_co_u32_e32 v78, vcc, s43, v48
	s_waitcnt vmcnt(0)
	v_lshlrev_b32_e32 v125, 16, v80
	v_lshlrev_b32_e32 v124, 16, v94
	v_and_b32_e32 v123, 0xffff0000, v80
	v_and_b32_e32 v122, 0xffff0000, v94
	v_lshlrev_b32_e32 v121, 16, v81
	v_lshlrev_b32_e32 v120, 16, v95
	v_and_b32_e32 v119, 0xffff0000, v81
	v_and_b32_e32 v118, 0xffff0000, v95
	v_lshlrev_b32_e32 v111, 16, v82
	v_lshlrev_b32_e32 v110, 16, v96
	v_and_b32_e32 v113, 0xffff0000, v82
	v_and_b32_e32 v112, 0xffff0000, v96
	v_lshlrev_b32_e32 v115, 16, v83
	v_lshlrev_b32_e32 v114, 16, v97
	v_and_b32_e32 v117, 0xffff0000, v83
	v_and_b32_e32 v116, 0xffff0000, v97
	v_pk_fma_f32 v[80:81], v[50:51], v[124:125], v[126:127]
	v_pk_fma_f32 v[82:83], v[22:23], v[122:123], v[128:129]
	v_pk_fma_f32 v[94:95], v[68:69], v[120:121], v[130:131]
	v_pk_fma_f32 v[96:97], v[24:25], v[118:119], v[132:133]
	v_pk_fma_f32 v[126:127], v[70:71], v[110:111], v[134:135]
	v_pk_fma_f32 v[128:129], v[18:19], v[112:113], v[136:137]
	v_pk_fma_f32 v[130:131], v[74:75], v[114:115], v[140:141]
	v_pk_fma_f32 v[132:133], v[20:21], v[116:117], v[146:147]
	v_mul_f32_e32 v35, 0xbfb8aa3b, v81
	v_mul_f32_e32 v86, 0xbfb8aa3b, v83
	v_mul_f32_e32 v134, 0xbfb8aa3b, v95
	v_mul_f32_e32 v135, 0xbfb8aa3b, v97
	v_mul_f32_e32 v136, 0xbfb8aa3b, v127
	v_mul_f32_e32 v137, 0xbfb8aa3b, v129
	v_mul_f32_e32 v140, 0xbfb8aa3b, v131
	v_mul_f32_e32 v141, 0xbfb8aa3b, v133
	v_exp_f32_e32 v35, v35
	v_exp_f32_e32 v86, v86
	v_exp_f32_e32 v134, v134
	v_exp_f32_e32 v135, v135
	v_exp_f32_e32 v136, v136
	v_exp_f32_e32 v137, v137
	v_exp_f32_e32 v140, v140
	v_exp_f32_e32 v141, v141
	v_add_f32_e32 v35, 1.0, v35
	v_add_f32_e32 v86, 1.0, v86
	v_add_f32_e32 v134, 1.0, v134
	v_add_f32_e32 v135, 1.0, v135
	v_add_f32_e32 v136, 1.0, v136
	v_add_f32_e32 v137, 1.0, v137
	v_add_f32_e32 v140, 1.0, v140
	v_add_f32_e32 v141, 1.0, v141
	v_rcp_f32_e32 v35, v35
	v_rcp_f32_e32 v86, v86
	v_rcp_f32_e32 v134, v134
	v_rcp_f32_e32 v135, v135
	v_rcp_f32_e32 v136, v136
	v_rcp_f32_e32 v137, v137
	v_rcp_f32_e32 v140, v140
	v_rcp_f32_e32 v141, v141
	v_mul_f32_e32 v35, v81, v35
	v_mul_f32_e32 v81, v83, v86
	v_mul_f32_e32 v83, v95, v134
	v_mul_f32_e32 v86, v97, v135
	v_mul_f32_e32 v95, v127, v136
	v_addc_co_u32_e32 v79, vcc, 0, v49, vcc
	v_mul_f32_e32 v97, v129, v137
	v_mul_f32_e32 v127, v131, v140
	v_mul_f32_e32 v129, v133, v141
	v_mul_f32_e32 v35, v80, v35
	v_mul_f32_e32 v80, v82, v81
	v_mul_f32_e32 v81, v94, v83
	v_mul_f32_e32 v82, v96, v86
	v_mul_f32_e32 v83, v126, v95
	v_add_co_u32_e32 v48, vcc, s44, v48
	v_mul_f32_e32 v86, v128, v97
	v_mul_f32_e32 v94, v130, v127
	v_mul_f32_e32 v95, v132, v129
	v_cvt_pk_bf16_f32 v80, v35, v80
	v_cvt_pk_bf16_f32 v81, v81, v82
	v_cvt_pk_bf16_f32 v82, v83, v86
	v_cvt_pk_bf16_f32 v83, v94, v95
	global_store_dwordx4 v[76:77], v[80:83], off offset:2560 sc1
	v_addc_co_u32_e32 v49, vcc, 0, v49, vcc
	global_load_dwordx4 v[76:79], v[78:79], off offset:2560 nt
	s_nop 0
	global_load_dwordx4 v[80:83], v[48:49], off offset:1536 nt
	v_pk_fma_f32 v[48:49], v[42:43], v[98:99], v[38:39]
	v_pk_fma_f32 v[94:95], v[6:7], v[100:101], v[30:31]
	v_pk_fma_f32 v[96:97], v[56:57], v[102:103], v[52:53]
	v_pk_fma_f32 v[98:99], v[8:9], v[104:105], v[32:33]
	v_pk_fma_f32 v[100:101], v[58:59], v[106:107], v[54:55]
	v_pk_fma_f32 v[102:103], v[2:3], v[108:109], v[26:27]
	v_pk_fma_f32 v[104:105], v[66:67], v[138:139], v[64:65]
	v_pk_fma_f32 v[106:107], v[4:5], v[158:159], v[28:29]
	v_pk_fma_f32 v[48:49], v[46:47], v[124:125], v[48:49]
	v_pk_fma_f32 v[126:127], v[14:15], v[122:123], v[94:95]
	v_pk_fma_f32 v[128:129], v[60:61], v[120:121], v[96:97]
	v_pk_fma_f32 v[130:131], v[16:17], v[118:119], v[98:99]
	v_pk_fma_f32 v[132:133], v[62:63], v[110:111], v[100:101]
	v_pk_fma_f32 v[134:135], v[10:11], v[112:113], v[102:103]
	v_pk_fma_f32 v[136:137], v[72:73], v[114:115], v[104:105]
	v_pk_fma_f32 v[138:139], v[12:13], v[116:117], v[106:107]
	v_add_co_u32_e32 v44, vcc, 0x190ea000, v44
	s_waitcnt vmcnt(0)
	v_lshlrev_b32_e32 v95, 16, v76
	v_lshlrev_b32_e32 v94, 16, v80
	v_and_b32_e32 v97, 0xffff0000, v76
	v_and_b32_e32 v96, 0xffff0000, v80
	v_lshlrev_b32_e32 v99, 16, v77
	v_lshlrev_b32_e32 v98, 16, v81
	v_and_b32_e32 v101, 0xffff0000, v77
	v_and_b32_e32 v100, 0xffff0000, v81
	v_lshlrev_b32_e32 v103, 16, v78
	v_lshlrev_b32_e32 v102, 16, v82
	v_and_b32_e32 v105, 0xffff0000, v78
	v_and_b32_e32 v104, 0xffff0000, v82
	v_lshlrev_b32_e32 v107, 16, v79
	v_lshlrev_b32_e32 v106, 16, v83
	v_and_b32_e32 v109, 0xffff0000, v79
	v_and_b32_e32 v108, 0xffff0000, v83
	v_pk_fma_f32 v[48:49], v[50:51], v[94:95], v[48:49]
	v_pk_fma_f32 v[76:77], v[22:23], v[96:97], v[126:127]
	v_pk_fma_f32 v[78:79], v[68:69], v[98:99], v[128:129]
	v_pk_fma_f32 v[80:81], v[24:25], v[100:101], v[130:131]
	v_pk_fma_f32 v[82:83], v[70:71], v[102:103], v[132:133]
	v_pk_fma_f32 v[126:127], v[18:19], v[104:105], v[134:135]
	v_pk_fma_f32 v[128:129], v[74:75], v[106:107], v[136:137]
	v_pk_fma_f32 v[130:131], v[20:21], v[108:109], v[138:139]
	v_mul_f32_e32 v35, 0xbfb8aa3b, v49
	v_mul_f32_e32 v86, 0xbfb8aa3b, v77
	v_mul_f32_e32 v132, 0xbfb8aa3b, v79
	v_mul_f32_e32 v133, 0xbfb8aa3b, v81
	v_mul_f32_e32 v134, 0xbfb8aa3b, v83
	v_mul_f32_e32 v135, 0xbfb8aa3b, v127
	v_mul_f32_e32 v136, 0xbfb8aa3b, v129
	v_mul_f32_e32 v137, 0xbfb8aa3b, v131
	v_exp_f32_e32 v35, v35
	v_exp_f32_e32 v86, v86
	v_exp_f32_e32 v132, v132
	v_exp_f32_e32 v133, v133
	v_exp_f32_e32 v134, v134
	v_exp_f32_e32 v135, v135
	v_exp_f32_e32 v136, v136
	v_exp_f32_e32 v137, v137
	v_add_f32_e32 v35, 1.0, v35
	v_add_f32_e32 v86, 1.0, v86
	v_add_f32_e32 v132, 1.0, v132
	v_add_f32_e32 v133, 1.0, v133
	v_add_f32_e32 v134, 1.0, v134
	v_add_f32_e32 v135, 1.0, v135
	v_add_f32_e32 v136, 1.0, v136
	v_add_f32_e32 v137, 1.0, v137
	v_rcp_f32_e32 v35, v35
	v_rcp_f32_e32 v86, v86
	v_rcp_f32_e32 v132, v132
	v_rcp_f32_e32 v133, v133
	v_rcp_f32_e32 v134, v134
	v_rcp_f32_e32 v135, v135
	v_rcp_f32_e32 v136, v136
	v_rcp_f32_e32 v137, v137
	v_mul_f32_e32 v35, v49, v35
	v_mul_f32_e32 v49, v77, v86
	v_mul_f32_e32 v77, v79, v132
	v_mul_f32_e32 v79, v81, v133
	v_mul_f32_e32 v81, v83, v134
	v_mul_f32_e32 v83, v127, v135
	v_addc_co_u32_e32 v45, vcc, 0, v45, vcc
	v_mul_f32_e32 v86, v129, v136
	v_mul_f32_e32 v127, v131, v137
	v_mul_f32_e32 v35, v48, v35
	v_mul_f32_e32 v48, v76, v49
	v_mul_f32_e32 v49, v78, v77
	v_mul_f32_e32 v77, v80, v79
	v_mul_f32_e32 v78, v82, v81
	v_mul_f32_e32 v79, v126, v83
	v_mul_f32_e32 v80, v128, v86
	v_mul_f32_e32 v81, v130, v127
	v_cvt_pk_bf16_f32 v76, v35, v48
	v_cvt_pk_bf16_f32 v77, v49, v77
	v_cvt_pk_bf16_f32 v78, v78, v79
	v_cvt_pk_bf16_f32 v79, v80, v81
	global_store_dwordx4 v[44:45], v[76:79], off offset:1536 sc1
	s_cbranch_scc0 .LBB0_2502
	v_lshl_add_u64 v[90:91], v[90:91], 0, s[6:7]
	v_cmp_lt_u64_e32 vcc, s[24:25], v[90:91]
	s_or_b64 s[20:21], vcc, s[20:21]
	s_andn2_b64 exec, exec, s[20:21]
	s_cbranch_execnz .LBB0_2493

.LBB0_2506:
	s_or_b64 exec, exec, s[26:27]
	v_mul_u32_u24_e32 v10, 0x1600, v10
	v_mov_b32_e32 v11, v7
	v_lshl_add_u64 v[8:9], v[8:9], 0, s[6:7]
	v_lshl_add_u64 v[10:11], v[10:11], 1, s[10:11]
	v_lshlrev_b32_e32 v6, 1, v6
	v_cmp_lt_u64_e32 vcc, s[24:25], v[8:9]
	v_lshl_add_u64 v[10:11], v[10:11], 0, v[6:7]
	s_or_b64 s[12:13], vcc, s[12:13]
	global_store_dwordx4 v[10:11], v[2:5], off sc1
	s_andn2_b64 exec, exec, s[12:13]
	s_cbranch_execz .LBB0_2511

.LBB0_2611:
	ds_read_b128 v[18:21], v12
	ds_read_b128 v[22:25], v12 offset:1024
	ds_read_b128 v[26:29], v12 offset:2048
	ds_read_b128 v[30:33], v12 offset:3072
	s_add_u32 s14, s22, s14
	s_addc_u32 s15, s23, s15
	s_and_b64 s[20:21], s[20:21], exec
	s_cselect_b32 s21, s15, s17
	s_cselect_b32 s20, s14, s16
	s_add_u32 s50, s16, 0x160080
	s_addc_u32 s51, s17, 0
	s_mov_b32 m0, s36
	v_lshl_add_u64 v[68:69], s[50:51], 0, v[132:133]
	ds_read_b128 v[36:39], v13
	ds_read_b128 v[40:43], v13 offset:1024
	ds_read_b128 v[44:47], v13 offset:2048
	ds_read_b128 v[48:51], v13 offset:3072
	ds_read_b128 v[52:55], v13 offset:4096
	ds_read_b128 v[56:59], v13 offset:5120
	ds_read_b128 v[60:63], v13 offset:6144
	ds_read_b128 v[64:67], v13 offset:7168
	global_load_lds_dwordx4 v[68:69], off
	v_lshl_add_u64 v[68:69], s[50:51], 0, v[134:135]
	s_mov_b32 m0, s37
	s_nop 0
	global_load_lds_dwordx4 v[68:69], off
	s_waitcnt lgkmcnt(8)
	s_barrier
	s_waitcnt lgkmcnt(0)
	s_setprio 1
	s_waitcnt lgkmcnt(0)
	v_mfma_f32_16x16x32_bf16 v[68:71], v[36:39], v[18:21], 0
	v_mfma_f32_16x16x32_bf16 v[76:79], v[44:47], v[18:21], 0
	v_mfma_f32_16x16x32_bf16 v[84:87], v[52:55], v[18:21], 0
	v_mfma_f32_16x16x32_bf16 v[18:21], v[60:63], v[18:21], 0
	v_mfma_f32_16x16x32_bf16 v[68:71], v[40:43], v[22:25], v[68:71]
	v_mfma_f32_16x16x32_bf16 v[72:75], v[36:39], v[26:29], 0
	v_mfma_f32_16x16x32_bf16 v[76:79], v[48:51], v[22:25], v[76:79]
	v_mfma_f32_16x16x32_bf16 v[80:83], v[44:47], v[26:29], 0
	v_mfma_f32_16x16x32_bf16 v[84:87], v[56:59], v[22:25], v[84:87]
	v_mfma_f32_16x16x32_bf16 v[88:91], v[52:55], v[26:29], 0
	v_mfma_f32_16x16x32_bf16 v[18:21], v[64:67], v[22:25], v[18:21]
	v_mfma_f32_16x16x32_bf16 v[22:25], v[60:63], v[26:29], 0
	v_mfma_f32_16x16x32_bf16 v[72:75], v[40:43], v[30:33], v[72:75]
	v_mfma_f32_16x16x32_bf16 v[80:83], v[48:51], v[30:33], v[80:83]
	v_mfma_f32_16x16x32_bf16 v[88:91], v[56:59], v[30:33], v[88:91]
	v_mfma_f32_16x16x32_bf16 v[22:25], v[64:67], v[30:33], v[22:25]
	s_setprio 0
	s_barrier
	v_lshl_add_u64 v[136:137], s[18:19], 0, v[132:133]
	s_mov_b32 m0, s38
	v_lshl_add_u64 v[100:101], v[136:137], 0, s[6:7]
	v_lshl_add_u64 v[138:139], s[18:19], 0, v[134:135]
	ds_read_b128 v[26:29], v14
	ds_read_b128 v[30:33], v14 offset:1024
	ds_read_b128 v[92:95], v14 offset:2048
	ds_read_b128 v[96:99], v14 offset:3072
	global_load_lds_dwordx4 v[100:101], off
	v_lshl_add_u64 v[100:101], v[138:139], 0, s[6:7]
	s_mov_b32 m0, s39
	s_nop 0
	global_load_lds_dwordx4 v[100:101], off
	s_barrier
	s_waitcnt lgkmcnt(0)
	s_setprio 1
	s_waitcnt lgkmcnt(0)
	v_mfma_f32_16x16x32_bf16 v[100:103], v[36:39], v[26:29], 0
	v_mfma_f32_16x16x32_bf16 v[36:39], v[36:39], v[92:95], 0
	v_mfma_f32_16x16x32_bf16 v[100:103], v[40:43], v[30:33], v[100:103]
	v_mfma_f32_16x16x32_bf16 v[36:39], v[40:43], v[96:99], v[36:39]
	v_mfma_f32_16x16x32_bf16 v[40:43], v[44:47], v[26:29], 0
	v_mfma_f32_16x16x32_bf16 v[44:47], v[44:47], v[92:95], 0
	v_mfma_f32_16x16x32_bf16 v[40:43], v[48:51], v[30:33], v[40:43]
	v_mfma_f32_16x16x32_bf16 v[44:47], v[48:51], v[96:99], v[44:47]
	v_mfma_f32_16x16x32_bf16 v[48:51], v[52:55], v[26:29], 0
	v_mfma_f32_16x16x32_bf16 v[26:29], v[60:63], v[26:29], 0
	v_mfma_f32_16x16x32_bf16 v[48:51], v[56:59], v[30:33], v[48:51]
	v_mfma_f32_16x16x32_bf16 v[52:55], v[52:55], v[92:95], 0
	v_mfma_f32_16x16x32_bf16 v[26:29], v[64:67], v[30:33], v[26:29]
	v_mfma_f32_16x16x32_bf16 v[30:33], v[60:63], v[92:95], 0
	v_mfma_f32_16x16x32_bf16 v[52:55], v[56:59], v[96:99], v[52:55]
	v_mfma_f32_16x16x32_bf16 v[30:33], v[64:67], v[96:99], v[30:33]
	s_setprio 0
	v_lshl_add_u64 v[140:141], s[16:17], 0, v[132:133]
	s_mov_b32 m0, s5
	v_lshl_add_u64 v[56:57], v[140:141], 0, s[6:7]
	v_lshl_add_u64 v[142:143], s[16:17], 0, v[134:135]
	s_barrier
	global_load_lds_dwordx4 v[56:57], off
	v_lshl_add_u64 v[56:57], v[142:143], 0, s[6:7]
	s_mov_b32 m0, s24
	s_nop 0
	global_load_lds_dwordx4 v[56:57], off
	s_barrier
	s_waitcnt lgkmcnt(0)
	s_setprio 1
	s_setprio 0
	s_barrier
	s_add_u32 s50, s18, 0x160100
	s_addc_u32 s51, s19, 0
	s_mov_b32 m0, s40
	v_lshl_add_u64 v[56:57], s[50:51], 0, v[132:133]
	global_load_lds_dwordx4 v[56:57], off
	v_lshl_add_u64 v[56:57], s[50:51], 0, v[134:135]
	s_mov_b32 m0, s41
	s_nop 0
	global_load_lds_dwordx4 v[56:57], off
	s_waitcnt vmcnt(6)
	s_barrier
	s_setprio 1
	s_setprio 0
	s_barrier
	ds_read_b128 v[56:59], v15
	ds_read_b128 v[60:63], v15 offset:1024
	ds_read_b128 v[64:67], v15 offset:2048
	ds_read_b128 v[92:95], v15 offset:3072
	s_add_u32 s50, s16, 0x160100
	s_addc_u32 s51, s17, 0
	s_mov_b32 m0, s25
	v_lshl_add_u64 v[144:145], s[50:51], 0, v[132:133]
	ds_read_b128 v[96:99], v13 offset:32768
	ds_read_b128 v[104:107], v13 offset:33792
	ds_read_b128 v[108:111], v13 offset:34816
	ds_read_b128 v[112:115], v13 offset:35840
	ds_read_b128 v[116:119], v13 offset:36864
	ds_read_b128 v[120:123], v13 offset:37888
	ds_read_b128 v[124:127], v13 offset:38912
	ds_read_b128 v[128:131], v13 offset:39936
	global_load_lds_dwordx4 v[144:145], off
	v_lshl_add_u64 v[144:145], s[50:51], 0, v[134:135]
	s_mov_b32 m0, s26
	s_nop 0
	global_load_lds_dwordx4 v[144:145], off
	s_waitcnt lgkmcnt(8)
	s_barrier
	s_waitcnt lgkmcnt(0)
	s_setprio 1
	s_waitcnt lgkmcnt(0)
	v_mfma_f32_16x16x32_bf16 v[68:71], v[96:99], v[56:59], v[68:71]
	v_mfma_f32_16x16x32_bf16 v[72:75], v[96:99], v[64:67], v[72:75]
	v_mfma_f32_16x16x32_bf16 v[76:79], v[108:111], v[56:59], v[76:79]
	v_mfma_f32_16x16x32_bf16 v[80:83], v[108:111], v[64:67], v[80:83]
	v_mfma_f32_16x16x32_bf16 v[84:87], v[116:119], v[56:59], v[84:87]
	v_mfma_f32_16x16x32_bf16 v[88:91], v[116:119], v[64:67], v[88:91]
	v_mfma_f32_16x16x32_bf16 v[18:21], v[124:127], v[56:59], v[18:21]
	v_mfma_f32_16x16x32_bf16 v[22:25], v[124:127], v[64:67], v[22:25]
	v_mfma_f32_16x16x32_bf16 v[68:71], v[104:107], v[60:63], v[68:71]
	v_mfma_f32_16x16x32_bf16 v[72:75], v[104:107], v[92:95], v[72:75]
	v_mfma_f32_16x16x32_bf16 v[76:79], v[112:115], v[60:63], v[76:79]
	v_mfma_f32_16x16x32_bf16 v[80:83], v[112:115], v[92:95], v[80:83]
	v_mfma_f32_16x16x32_bf16 v[84:87], v[120:123], v[60:63], v[84:87]
	v_mfma_f32_16x16x32_bf16 v[88:91], v[120:123], v[92:95], v[88:91]
	v_mfma_f32_16x16x32_bf16 v[18:21], v[128:131], v[60:63], v[18:21]
	v_mfma_f32_16x16x32_bf16 v[22:25], v[128:131], v[92:95], v[22:25]
	s_setprio 0
	s_barrier
	s_mov_b32 m0, s42
	v_lshl_add_u64 v[136:137], v[136:137], 0, s[8:9]
	ds_read_b128 v[56:59], v16
	ds_read_b128 v[60:63], v16 offset:1024
	ds_read_b128 v[64:67], v16 offset:2048
	ds_read_b128 v[92:95], v16 offset:3072
	global_load_lds_dwordx4 v[136:137], off
	v_lshl_add_u64 v[136:137], v[138:139], 0, s[8:9]
	s_mov_b32 m0, s43
	s_nop 0
	global_load_lds_dwordx4 v[136:137], off
	s_barrier
	s_waitcnt lgkmcnt(0)
	s_setprio 1
	s_waitcnt lgkmcnt(0)
	v_mfma_f32_16x16x32_bf16 v[100:103], v[96:99], v[56:59], v[100:103]
	v_mfma_f32_16x16x32_bf16 v[36:39], v[96:99], v[64:67], v[36:39]
	v_mfma_f32_16x16x32_bf16 v[40:43], v[108:111], v[56:59], v[40:43]
	v_mfma_f32_16x16x32_bf16 v[44:47], v[108:111], v[64:67], v[44:47]
	v_mfma_f32_16x16x32_bf16 v[48:51], v[116:119], v[56:59], v[48:51]
	v_mfma_f32_16x16x32_bf16 v[52:55], v[116:119], v[64:67], v[52:55]
	v_mfma_f32_16x16x32_bf16 v[26:29], v[124:127], v[56:59], v[26:29]
	v_mfma_f32_16x16x32_bf16 v[30:33], v[124:127], v[64:67], v[30:33]
	v_mfma_f32_16x16x32_bf16 v[100:103], v[104:107], v[60:63], v[100:103]
	v_mfma_f32_16x16x32_bf16 v[36:39], v[104:107], v[92:95], v[36:39]
	v_mfma_f32_16x16x32_bf16 v[40:43], v[112:115], v[60:63], v[40:43]
	v_mfma_f32_16x16x32_bf16 v[44:47], v[112:115], v[92:95], v[44:47]
	v_mfma_f32_16x16x32_bf16 v[48:51], v[120:123], v[60:63], v[48:51]
	v_mfma_f32_16x16x32_bf16 v[52:55], v[120:123], v[92:95], v[52:55]
	v_mfma_f32_16x16x32_bf16 v[26:29], v[128:131], v[60:63], v[26:29]
	v_mfma_f32_16x16x32_bf16 v[30:33], v[128:131], v[92:95], v[30:33]
	s_setprio 0
	s_mov_b32 m0, s29
	v_lshl_add_u64 v[56:57], v[140:141], 0, s[8:9]
	s_barrier
	global_load_lds_dwordx4 v[56:57], off
	v_lshl_add_u64 v[56:57], v[142:143], 0, s[8:9]
	s_mov_b32 m0, s30
	s_nop 0
	global_load_lds_dwordx4 v[56:57], off
	s_barrier
	s_waitcnt lgkmcnt(0)
	s_setprio 1
	s_setprio 0
	s_barrier
	s_add_u32 s18, s18, 0x160180
	s_addc_u32 s19, s19, 0
	s_mov_b32 m0, s44
	v_lshl_add_u64 v[56:57], s[18:19], 0, v[132:133]
	global_load_lds_dwordx4 v[56:57], off
	v_lshl_add_u64 v[56:57], s[18:19], 0, v[134:135]
	s_mov_b32 m0, s45
	s_nop 0
	global_load_lds_dwordx4 v[56:57], off
	s_waitcnt vmcnt(6)
	s_barrier
	s_setprio 1
	s_setprio 0
	s_barrier
	ds_read_b128 v[56:59], v12
	ds_read_b128 v[60:63], v12 offset:1024
	ds_read_b128 v[64:67], v12 offset:2048
	ds_read_b128 v[92:95], v12 offset:3072
	s_add_u32 s16, s16, 0x160180
	s_addc_u32 s17, s17, 0
	s_mov_b32 m0, s36
	v_lshl_add_u64 v[136:137], s[16:17], 0, v[132:133]
	ds_read_b128 v[96:99], v13
	ds_read_b128 v[104:107], v13 offset:1024
	ds_read_b128 v[108:111], v13 offset:2048
	ds_read_b128 v[112:115], v13 offset:3072
	ds_read_b128 v[116:119], v13 offset:4096
	ds_read_b128 v[120:123], v13 offset:5120
	ds_read_b128 v[124:127], v13 offset:6144
	ds_read_b128 v[128:131], v13 offset:7168
	global_load_lds_dwordx4 v[136:137], off
	v_lshl_add_u64 v[136:137], s[16:17], 0, v[134:135]
	s_mov_b32 m0, s37
	s_nop 0
	global_load_lds_dwordx4 v[136:137], off
	s_waitcnt lgkmcnt(8)
	s_barrier
	s_waitcnt lgkmcnt(0)
	s_setprio 1
	s_waitcnt lgkmcnt(0)
	v_mfma_f32_16x16x32_bf16 v[68:71], v[96:99], v[56:59], v[68:71]
	v_mfma_f32_16x16x32_bf16 v[72:75], v[96:99], v[64:67], v[72:75]
	v_mfma_f32_16x16x32_bf16 v[76:79], v[108:111], v[56:59], v[76:79]
	v_mfma_f32_16x16x32_bf16 v[80:83], v[108:111], v[64:67], v[80:83]
	v_mfma_f32_16x16x32_bf16 v[84:87], v[116:119], v[56:59], v[84:87]
	v_mfma_f32_16x16x32_bf16 v[88:91], v[116:119], v[64:67], v[88:91]
	v_mfma_f32_16x16x32_bf16 v[18:21], v[124:127], v[56:59], v[18:21]
	v_mfma_f32_16x16x32_bf16 v[22:25], v[124:127], v[64:67], v[22:25]
	v_mfma_f32_16x16x32_bf16 v[68:71], v[104:107], v[60:63], v[68:71]
	v_mfma_f32_16x16x32_bf16 v[72:75], v[104:107], v[92:95], v[72:75]
	v_mfma_f32_16x16x32_bf16 v[76:79], v[112:115], v[60:63], v[76:79]
	v_mfma_f32_16x16x32_bf16 v[80:83], v[112:115], v[92:95], v[80:83]
	v_mfma_f32_16x16x32_bf16 v[84:87], v[120:123], v[60:63], v[84:87]
	v_mfma_f32_16x16x32_bf16 v[88:91], v[120:123], v[92:95], v[88:91]
	v_mfma_f32_16x16x32_bf16 v[18:21], v[128:131], v[60:63], v[18:21]
	v_mfma_f32_16x16x32_bf16 v[22:25], v[128:131], v[92:95], v[22:25]
	s_setprio 0
	s_barrier
	s_mov_b32 m0, s38
	v_lshl_add_u64 v[136:137], s[10:11], 0, v[132:133]
	ds_read_b128 v[56:59], v14
	ds_read_b128 v[60:63], v14 offset:1024
	ds_read_b128 v[64:67], v14 offset:2048
	ds_read_b128 v[92:95], v14 offset:3072
	global_load_lds_dwordx4 v[136:137], off
	v_lshl_add_u64 v[138:139], s[10:11], 0, v[134:135]
	s_mov_b32 m0, s39
	s_nop 0
	global_load_lds_dwordx4 v[138:139], off
	s_barrier
	s_waitcnt lgkmcnt(0)
	s_setprio 1
	s_waitcnt lgkmcnt(0)
	v_mfma_f32_16x16x32_bf16 v[100:103], v[96:99], v[56:59], v[100:103]
	v_mfma_f32_16x16x32_bf16 v[36:39], v[96:99], v[64:67], v[36:39]
	v_mfma_f32_16x16x32_bf16 v[40:43], v[108:111], v[56:59], v[40:43]
	v_mfma_f32_16x16x32_bf16 v[44:47], v[108:111], v[64:67], v[44:47]
	v_mfma_f32_16x16x32_bf16 v[48:51], v[116:119], v[56:59], v[48:51]
	v_mfma_f32_16x16x32_bf16 v[52:55], v[116:119], v[64:67], v[52:55]
	v_mfma_f32_16x16x32_bf16 v[26:29], v[124:127], v[56:59], v[26:29]
	v_mfma_f32_16x16x32_bf16 v[30:33], v[124:127], v[64:67], v[30:33]
	v_mfma_f32_16x16x32_bf16 v[100:103], v[104:107], v[60:63], v[100:103]
	v_mfma_f32_16x16x32_bf16 v[36:39], v[104:107], v[92:95], v[36:39]
	v_mfma_f32_16x16x32_bf16 v[40:43], v[112:115], v[60:63], v[40:43]
	v_mfma_f32_16x16x32_bf16 v[44:47], v[112:115], v[92:95], v[44:47]
	v_mfma_f32_16x16x32_bf16 v[48:51], v[120:123], v[60:63], v[48:51]
	v_mfma_f32_16x16x32_bf16 v[52:55], v[120:123], v[92:95], v[52:55]
	v_mfma_f32_16x16x32_bf16 v[26:29], v[128:131], v[60:63], v[26:29]
	v_mfma_f32_16x16x32_bf16 v[30:33], v[128:131], v[92:95], v[30:33]
	s_setprio 0
	s_mov_b32 m0, s5
	v_lshl_add_u64 v[140:141], s[20:21], 0, v[132:133]
	s_barrier
	global_load_lds_dwordx4 v[140:141], off
	v_lshl_add_u64 v[142:143], s[20:21], 0, v[134:135]
	s_mov_b32 m0, s24
	s_nop 0
	global_load_lds_dwordx4 v[142:143], off
	s_barrier
	s_waitcnt lgkmcnt(0)
	s_setprio 1
	s_setprio 0
	s_barrier
	s_add_u32 s16, s10, 0x160000
	s_addc_u32 s17, s11, 0
	s_mov_b32 m0, s40
	v_lshl_add_u64 v[56:57], s[16:17], 0, v[132:133]
	global_load_lds_dwordx4 v[56:57], off
	v_lshl_add_u64 v[56:57], s[16:17], 0, v[134:135]
	s_mov_b32 m0, s41
	s_nop 0
	global_load_lds_dwordx4 v[56:57], off
	s_waitcnt vmcnt(6)
	s_barrier
	s_setprio 1
	s_setprio 0
	s_barrier
	ds_read_b128 v[56:59], v15
	ds_read_b128 v[60:63], v15 offset:1024
	ds_read_b128 v[64:67], v15 offset:2048
	ds_read_b128 v[92:95], v15 offset:3072
	s_add_u32 s16, s20, 0x160000
	s_addc_u32 s17, s21, 0
	s_mov_b32 m0, s25
	v_lshl_add_u64 v[144:145], s[16:17], 0, v[132:133]
	ds_read_b128 v[96:99], v13 offset:32768
	ds_read_b128 v[104:107], v13 offset:33792
	ds_read_b128 v[108:111], v13 offset:34816
	ds_read_b128 v[112:115], v13 offset:35840
	ds_read_b128 v[116:119], v13 offset:36864
	ds_read_b128 v[120:123], v13 offset:37888
	ds_read_b128 v[124:127], v13 offset:38912
	ds_read_b128 v[128:131], v13 offset:39936
	global_load_lds_dwordx4 v[144:145], off
	v_lshl_add_u64 v[144:145], s[16:17], 0, v[134:135]
	s_mov_b32 m0, s26
	s_nop 0
	global_load_lds_dwordx4 v[144:145], off
	s_waitcnt lgkmcnt(8)
	s_barrier
	s_waitcnt lgkmcnt(0)
	s_setprio 1
	s_waitcnt lgkmcnt(0)
	v_mfma_f32_16x16x32_bf16 v[68:71], v[96:99], v[56:59], v[68:71]
	v_mfma_f32_16x16x32_bf16 v[72:75], v[96:99], v[64:67], v[72:75]
	v_mfma_f32_16x16x32_bf16 v[76:79], v[108:111], v[56:59], v[76:79]
	v_mfma_f32_16x16x32_bf16 v[80:83], v[108:111], v[64:67], v[80:83]
	v_mfma_f32_16x16x32_bf16 v[84:87], v[116:119], v[56:59], v[84:87]
	v_mfma_f32_16x16x32_bf16 v[88:91], v[116:119], v[64:67], v[88:91]
	v_mfma_f32_16x16x32_bf16 v[18:21], v[124:127], v[56:59], v[18:21]
	v_mfma_f32_16x16x32_bf16 v[22:25], v[124:127], v[64:67], v[22:25]
	v_mfma_f32_16x16x32_bf16 v[68:71], v[104:107], v[60:63], v[68:71]
	v_mfma_f32_16x16x32_bf16 v[72:75], v[104:107], v[92:95], v[72:75]
	v_mfma_f32_16x16x32_bf16 v[76:79], v[112:115], v[60:63], v[76:79]
	v_mfma_f32_16x16x32_bf16 v[80:83], v[112:115], v[92:95], v[80:83]
	v_mfma_f32_16x16x32_bf16 v[84:87], v[120:123], v[60:63], v[84:87]
	v_mfma_f32_16x16x32_bf16 v[88:91], v[120:123], v[92:95], v[88:91]
	v_mfma_f32_16x16x32_bf16 v[18:21], v[128:131], v[60:63], v[18:21]
	v_mfma_f32_16x16x32_bf16 v[22:25], v[128:131], v[92:95], v[22:25]
	s_setprio 0
	s_barrier
	s_mov_b32 m0, s42
	v_lshl_add_u64 v[136:137], v[136:137], 0, s[0:1]
	ds_read_b128 v[56:59], v16
	ds_read_b128 v[60:63], v16 offset:1024
	ds_read_b128 v[64:67], v16 offset:2048
	ds_read_b128 v[92:95], v16 offset:3072
	global_load_lds_dwordx4 v[136:137], off
	v_lshl_add_u64 v[136:137], v[138:139], 0, s[0:1]
	s_mov_b32 m0, s43
	s_nop 0
	global_load_lds_dwordx4 v[136:137], off
	s_barrier
	s_waitcnt lgkmcnt(0)
	s_setprio 1
	s_waitcnt lgkmcnt(0)
	v_mfma_f32_16x16x32_bf16 v[100:103], v[96:99], v[56:59], v[100:103]
	v_mfma_f32_16x16x32_bf16 v[36:39], v[96:99], v[64:67], v[36:39]
	v_mfma_f32_16x16x32_bf16 v[40:43], v[108:111], v[56:59], v[40:43]
	v_mfma_f32_16x16x32_bf16 v[44:47], v[108:111], v[64:67], v[44:47]
	v_mfma_f32_16x16x32_bf16 v[48:51], v[116:119], v[56:59], v[48:51]
	v_mfma_f32_16x16x32_bf16 v[52:55], v[116:119], v[64:67], v[52:55]
	v_mfma_f32_16x16x32_bf16 v[26:29], v[124:127], v[56:59], v[26:29]
	v_mfma_f32_16x16x32_bf16 v[30:33], v[124:127], v[64:67], v[30:33]
	v_mfma_f32_16x16x32_bf16 v[100:103], v[104:107], v[60:63], v[100:103]
	v_mfma_f32_16x16x32_bf16 v[36:39], v[104:107], v[92:95], v[36:39]
	v_mfma_f32_16x16x32_bf16 v[40:43], v[112:115], v[60:63], v[40:43]
	v_mfma_f32_16x16x32_bf16 v[44:47], v[112:115], v[92:95], v[44:47]
	v_mfma_f32_16x16x32_bf16 v[48:51], v[120:123], v[60:63], v[48:51]
	v_mfma_f32_16x16x32_bf16 v[52:55], v[120:123], v[92:95], v[52:55]
	v_mfma_f32_16x16x32_bf16 v[26:29], v[128:131], v[60:63], v[26:29]
	v_mfma_f32_16x16x32_bf16 v[30:33], v[128:131], v[92:95], v[30:33]
	s_setprio 0
	s_mov_b32 m0, s29
	v_lshl_add_u64 v[56:57], v[140:141], 0, s[0:1]
	s_barrier
	global_load_lds_dwordx4 v[56:57], off
	v_lshl_add_u64 v[56:57], v[142:143], 0, s[0:1]
	s_mov_b32 m0, s30
	s_nop 0
	global_load_lds_dwordx4 v[56:57], off
	s_barrier
	s_waitcnt lgkmcnt(0)
	s_setprio 1
	s_setprio 0
	s_barrier
	s_add_u32 s16, s10, 0x160080
	s_addc_u32 s17, s11, 0
	s_mov_b32 m0, s44
	v_lshl_add_u64 v[56:57], s[16:17], 0, v[132:133]
	global_load_lds_dwordx4 v[56:57], off
	v_lshl_add_u64 v[56:57], s[16:17], 0, v[134:135]
	s_mov_b32 m0, s45
	s_nop 0
	global_load_lds_dwordx4 v[56:57], off
	s_waitcnt vmcnt(6)
	s_barrier
	s_setprio 1
	s_setprio 0
	v_lshl_or_b32 v2, s27, 8, v1
	v_lshlrev_b64 v[56:57], 2, v[2:3]
	v_lshl_add_u64 v[58:59], v[4:5], 0, v[56:57]
	s_barrier
	v_mov_b32_e32 v62, 0x2000
	v_mov_b32_e32 v63, 0
	v_mov_b32_e32 v56, 0x1a000
	v_mov_b32_e32 v57, 0
	v_mbcnt_lo_u32_b32 v60, -1, 0
	v_mbcnt_hi_u32_b32 v60, -1, v60
	v_and_b32_e32 v61, 15, v60
	v_lshrrev_b32_e32 v60, 4, v60
	v_lshlrev_b32_e32 v60, 2, v60
	v_sub_u32_e32 v60, v60, v61
	v_mul_i32_i24_e32 v60, 0x1ffc, v60
	v_ashrrev_i32_e32 v61, 31, v60
	v_lshl_add_u64 v[58:59], v[60:61], 0, v[58:59]
	global_atomic_add_f32 v[58:59], v68, off
	global_atomic_add_f32 v[58:59], v72, off offset:64
	global_atomic_add_f32 v[58:59], v100, off offset:512
	global_atomic_add_f32 v[58:59], v36, off offset:576
	v_lshl_add_u64 v[60:61], v[58:59], 0, v[62:63]
	global_atomic_add_f32 v[60:61], v69, off
	global_atomic_add_f32 v[60:61], v73, off offset:64
	global_atomic_add_f32 v[60:61], v101, off offset:512
	global_atomic_add_f32 v[60:61], v37, off offset:576
	v_lshl_add_u64 v[58:59], v[60:61], 0, v[62:63]
	global_atomic_add_f32 v[58:59], v70, off
	global_atomic_add_f32 v[58:59], v74, off offset:64
	global_atomic_add_f32 v[58:59], v102, off offset:512
	global_atomic_add_f32 v[58:59], v38, off offset:576
	v_lshl_add_u64 v[60:61], v[58:59], 0, v[62:63]
	global_atomic_add_f32 v[60:61], v71, off
	global_atomic_add_f32 v[60:61], v75, off offset:64
	global_atomic_add_f32 v[60:61], v103, off offset:512
	global_atomic_add_f32 v[60:61], v39, off offset:576
	v_lshl_add_u64 v[58:59], v[60:61], 0, v[56:57]
	global_atomic_add_f32 v[58:59], v76, off
	global_atomic_add_f32 v[58:59], v80, off offset:64
	global_atomic_add_f32 v[58:59], v40, off offset:512
	global_atomic_add_f32 v[58:59], v44, off offset:576
	v_lshl_add_u64 v[60:61], v[58:59], 0, v[62:63]
	global_atomic_add_f32 v[60:61], v77, off
	global_atomic_add_f32 v[60:61], v81, off offset:64
	global_atomic_add_f32 v[60:61], v41, off offset:512
	global_atomic_add_f32 v[60:61], v45, off offset:576
	v_lshl_add_u64 v[58:59], v[60:61], 0, v[62:63]
	global_atomic_add_f32 v[58:59], v78, off
	global_atomic_add_f32 v[58:59], v82, off offset:64
	global_atomic_add_f32 v[58:59], v42, off offset:512
	global_atomic_add_f32 v[58:59], v46, off offset:576
	v_lshl_add_u64 v[60:61], v[58:59], 0, v[62:63]
	global_atomic_add_f32 v[60:61], v79, off
	global_atomic_add_f32 v[60:61], v83, off offset:64
	global_atomic_add_f32 v[60:61], v43, off offset:512
	global_atomic_add_f32 v[60:61], v47, off offset:576
	v_lshl_add_u64 v[58:59], v[60:61], 0, v[56:57]
	global_atomic_add_f32 v[58:59], v84, off
	global_atomic_add_f32 v[58:59], v88, off offset:64
	global_atomic_add_f32 v[58:59], v48, off offset:512
	global_atomic_add_f32 v[58:59], v52, off offset:576
	v_lshl_add_u64 v[60:61], v[58:59], 0, v[62:63]
	global_atomic_add_f32 v[60:61], v85, off
	global_atomic_add_f32 v[60:61], v89, off offset:64
	global_atomic_add_f32 v[60:61], v49, off offset:512
	global_atomic_add_f32 v[60:61], v53, off offset:576
	v_lshl_add_u64 v[58:59], v[60:61], 0, v[62:63]
	global_atomic_add_f32 v[58:59], v86, off
	global_atomic_add_f32 v[58:59], v90, off offset:64
	global_atomic_add_f32 v[58:59], v50, off offset:512
	global_atomic_add_f32 v[58:59], v54, off offset:576
	v_lshl_add_u64 v[60:61], v[58:59], 0, v[62:63]
	global_atomic_add_f32 v[60:61], v87, off
	global_atomic_add_f32 v[60:61], v91, off offset:64
	global_atomic_add_f32 v[60:61], v51, off offset:512
	global_atomic_add_f32 v[60:61], v55, off offset:576
	v_lshl_add_u64 v[58:59], v[60:61], 0, v[56:57]
	global_atomic_add_f32 v[58:59], v18, off
	global_atomic_add_f32 v[58:59], v22, off offset:64
	global_atomic_add_f32 v[58:59], v26, off offset:512
	global_atomic_add_f32 v[58:59], v30, off offset:576
	v_lshl_add_u64 v[60:61], v[58:59], 0, v[62:63]
	global_atomic_add_f32 v[60:61], v19, off
	global_atomic_add_f32 v[60:61], v23, off offset:64
	global_atomic_add_f32 v[60:61], v27, off offset:512
	global_atomic_add_f32 v[60:61], v31, off offset:576
	v_lshl_add_u64 v[58:59], v[60:61], 0, v[62:63]
	global_atomic_add_f32 v[58:59], v20, off
	global_atomic_add_f32 v[58:59], v24, off offset:64
	global_atomic_add_f32 v[58:59], v28, off offset:512
	global_atomic_add_f32 v[58:59], v32, off offset:576
	v_lshl_add_u64 v[60:61], v[58:59], 0, v[62:63]
	global_atomic_add_f32 v[60:61], v21, off
	global_atomic_add_f32 v[60:61], v25, off offset:64
	global_atomic_add_f32 v[60:61], v29, off offset:512
	global_atomic_add_f32 v[60:61], v33, off offset:576
	s_add_i32 s31, s31, s33
	s_andn2_b64 vcc, exec, s[12:13]
	s_mov_b32 s27, s48
	s_mov_b64 s[18:19], s[10:11]
	s_mov_b64 s[16:17], s[14:15]
	s_cbranch_vccz .LBB0_2614

	.amdhsa_kernel _Z10fwd_kernel6Params
		.amdhsa_group_segment_fixed_size 0
		.amdhsa_private_segment_fixed_size 0
		.amdhsa_kernarg_size 568
		.amdhsa_user_sgpr_count 2
		.amdhsa_user_sgpr_dispatch_ptr 0
		.amdhsa_user_sgpr_queue_ptr 0
		.amdhsa_user_sgpr_kernarg_segment_ptr 1
		.amdhsa_user_sgpr_dispatch_id 0
		.amdhsa_user_sgpr_kernarg_preload_length 0
		.amdhsa_user_sgpr_kernarg_preload_offset 0
		.amdhsa_user_sgpr_private_segment_size 0
		.amdhsa_uses_dynamic_stack 0
		.amdhsa_enable_private_segment 0
		.amdhsa_system_sgpr_workgroup_id_x 1
		.amdhsa_system_sgpr_workgroup_id_y 0
		.amdhsa_system_sgpr_workgroup_id_z 0
		.amdhsa_system_sgpr_workgroup_info 0
		.amdhsa_system_vgpr_workitem_id 2
		.amdhsa_next_free_vgpr 256
		.amdhsa_next_free_sgpr 99
		.amdhsa_accum_offset 256
		.amdhsa_reserve_vcc 1
		.amdhsa_float_round_mode_32 0
		.amdhsa_float_round_mode_16_64 0
		.amdhsa_float_denorm_mode_32 3
		.amdhsa_float_denorm_mode_16_64 3
		.amdhsa_dx10_clamp 1
		.amdhsa_ieee_mode 1
		.amdhsa_fp16_overflow 0
		.amdhsa_tg_split 0
		.amdhsa_exception_fp_ieee_invalid_op 0
		.amdhsa_exception_fp_denorm_src 0
		.amdhsa_exception_fp_ieee_div_zero 0
		.amdhsa_exception_fp_ieee_overflow 0
		.amdhsa_exception_fp_ieee_underflow 0
		.amdhsa_exception_fp_ieee_inexact 0
		.amdhsa_exception_int_div_zero 0
	.end_amdhsa_kernel

amdhsa.kernels:
  - .agpr_count:     0
    .args:
      - .offset:         0
        .size:           312
        .value_kind:     by_value
      - .offset:         312
        .size:           4
        .value_kind:     hidden_block_count_x
      - .offset:         316
        .size:           4
        .value_kind:     hidden_block_count_y
      - .offset:         320
        .size:           4
        .value_kind:     hidden_block_count_z
      - .offset:         324
        .size:           2
        .value_kind:     hidden_group_size_x
      - .offset:         326
        .size:           2
        .value_kind:     hidden_group_size_y
      - .offset:         328
        .size:           2
        .value_kind:     hidden_group_size_z
      - .offset:         330
        .size:           2
        .value_kind:     hidden_remainder_x
      - .offset:         332
        .size:           2
        .value_kind:     hidden_remainder_y
      - .offset:         334
        .size:           2
        .value_kind:     hidden_remainder_z
      - .offset:         352
        .size:           8
        .value_kind:     hidden_global_offset_x
      - .offset:         360
        .size:           8
        .value_kind:     hidden_global_offset_y
      - .offset:         368
        .size:           8
        .value_kind:     hidden_global_offset_z
      - .offset:         376
        .size:           2
        .value_kind:     hidden_grid_dims
      - .offset:         400
        .size:           8
        .value_kind:     hidden_multigrid_sync_arg
      - .offset:         432
        .size:           4
        .value_kind:     hidden_dynamic_lds_size
    .group_segment_fixed_size: 0
    .kernarg_segment_align: 8
    .kernarg_segment_size: 568
    .language:       OpenCL C
    .language_version:
      - 2
      - 0
    .max_flat_workgroup_size: 512
    .name:           _Z10fwd_kernel6Params
    .private_segment_fixed_size: 0
    .sgpr_count:     105
    .sgpr_spill_count: 68
    .symbol:         _Z10fwd_kernel6Params.kd
    .uniform_work_group_size: 1
    .uses_dynamic_stack: false
    .vgpr_count:     256
    .vgpr_spill_count: 0
    .wavefront_size: 64
